# GEMM K-loops: snake MFMA order within each 8-MFMA group (every adjacent pair shares an operand)
# speedup vs baseline: 1.0021x; 1.0021x over previous
.LBB0_383:
	s_ashr_i32 s67, s66, 31
	s_lshl_b64 s[26:27], s[66:67], 19
	s_add_u32 s26, s40, s26
	s_addc_u32 s27, s41, s27
	s_and_b64 s[34:35], s[8:9], exec
	s_cselect_b32 s34, s27, s5
	s_cselect_b32 s35, s26, s4
	s_ashr_i32 s29, s28, 31
	s_lshl_b64 s[38:39], s[28:29], 19
	s_add_u32 s62, s10, s38
	s_addc_u32 s63, s11, s39
	s_and_b64 s[38:39], s[8:9], exec
	s_cselect_b32 s29, s63, s83
	s_cselect_b32 s38, s62, s82
	s_add_u32 s39, s82, 0x100
	s_addc_u32 s67, s83, 0
	s_mov_b32 s94, -2
	s_mov_b64 vcc, 0
	v_lshl_add_u64 v[132:133], s[4:5], 0, v[168:169]
	ds_read_b128 v[134:137], v199
	ds_read_b128 v[138:141], v200
	ds_read_b128 v[142:145], v201
	ds_read_b128 v[146:149], v202
	ds_read_b128 v[150:153], v203
	ds_read_b128 v[174:177], v204
	ds_read_b128 v[178:181], v205
	ds_read_b128 v[182:185], v206
	s_add_u32 s24, s4, vcc_lo
	s_addc_u32 s25, s5, vcc_hi
	s_add_u32 s24, s24, 0x100
	s_addc_u32 s25, s25, 0
	s_add_u32 s82, s39, vcc_lo
	s_addc_u32 s83, s67, vcc_hi
	s_cmpk_eq_i32 vcc_lo, 0x700
	s_cselect_b32 s87, s29, s83
	s_cselect_b32 s86, s38, s82
	s_cselect_b32 s83, s34, s25
	s_cselect_b32 s82, s35, s24
	v_lshl_add_u64 v[154:155], v[132:133], 0, vcc
	v_lshl_add_u64 v[250:251], v[154:155], 0, s[48:49]
	s_add_i32 m0, s79, 0x8000
	s_mov_b64 s[24:25], 0x20080
	ds_read_b128 v[218:221], v207
	ds_read_b128 v[222:225], v207 offset:2048
	ds_read_b128 v[226:229], v208
	ds_read_b128 v[230:233], v208 offset:2048
	ds_read_b128 v[234:237], v207 offset:4096
	ds_read_b128 v[238:241], v207 offset:6144
	ds_read_b128 v[242:245], v208 offset:4096
	ds_read_b128 v[246:249], v208 offset:6144
	global_load_lds_dwordx4 v[250:251], off
	v_lshl_add_u64 v[250:251], v[154:155], 0, s[24:25]
	s_add_i32 m0, s79, 0xa000
	s_mov_b64 s[24:25], 0x60080
	global_load_lds_dwordx4 v[250:251], off
	v_lshl_add_u64 v[250:251], v[154:155], 0, s[50:51]
	s_add_i32 m0, s79, 0xc000
	v_lshl_add_u64 v[154:155], v[154:155], 0, s[24:25]
	global_load_lds_dwordx4 v[250:251], off
	s_add_i32 m0, s79, 0xe000
	s_nop 0
	global_load_lds_dwordx4 v[154:155], off
	s_waitcnt lgkmcnt(0)
	s_barrier
	v_mfma_f32_16x16x32_bf16 v[128:131], v[134:137], v[218:221], 0
	v_mfma_f32_16x16x32_bf16 v[124:127], v[142:145], v[218:221], 0
	v_mfma_f32_16x16x32_bf16 v[108:111], v[142:145], v[222:225], 0
	v_mfma_f32_16x16x32_bf16 v[112:115], v[134:137], v[222:225], 0
	v_mfma_f32_16x16x32_bf16 v[96:99], v[134:137], v[234:237], 0
	v_mfma_f32_16x16x32_bf16 v[92:95], v[142:145], v[234:237], 0
	v_mfma_f32_16x16x32_bf16 v[76:79], v[142:145], v[238:241], 0
	v_mfma_f32_16x16x32_bf16 v[80:83], v[134:137], v[238:241], 0
	v_mfma_f32_16x16x32_bf16 v[128:131], v[138:141], v[226:229], v[128:131]
	v_mfma_f32_16x16x32_bf16 v[124:127], v[146:149], v[226:229], v[124:127]
	v_mfma_f32_16x16x32_bf16 v[108:111], v[146:149], v[230:233], v[108:111]
	v_mfma_f32_16x16x32_bf16 v[112:115], v[138:141], v[230:233], v[112:115]
	v_mfma_f32_16x16x32_bf16 v[96:99], v[138:141], v[242:245], v[96:99]
	v_mfma_f32_16x16x32_bf16 v[92:95], v[146:149], v[242:245], v[92:95]
	v_mfma_f32_16x16x32_bf16 v[76:79], v[146:149], v[246:249], v[76:79]
	v_mfma_f32_16x16x32_bf16 v[80:83], v[138:141], v[246:249], v[80:83]
	v_mfma_f32_16x16x32_bf16 v[120:123], v[150:153], v[218:221], 0
	v_mfma_f32_16x16x32_bf16 v[116:119], v[178:181], v[218:221], 0
	v_mfma_f32_16x16x32_bf16 v[100:103], v[178:181], v[222:225], 0
	v_mfma_f32_16x16x32_bf16 v[104:107], v[150:153], v[222:225], 0
	v_mfma_f32_16x16x32_bf16 v[88:91], v[150:153], v[234:237], 0
	v_mfma_f32_16x16x32_bf16 v[84:87], v[178:181], v[234:237], 0
	v_mfma_f32_16x16x32_bf16 v[68:71], v[178:181], v[238:241], 0
	v_mfma_f32_16x16x32_bf16 v[72:75], v[150:153], v[238:241], 0
	v_mfma_f32_16x16x32_bf16 v[120:123], v[174:177], v[226:229], v[120:123]
	v_mfma_f32_16x16x32_bf16 v[116:119], v[182:185], v[226:229], v[116:119]
	v_mfma_f32_16x16x32_bf16 v[100:103], v[182:185], v[230:233], v[100:103]
	v_mfma_f32_16x16x32_bf16 v[104:107], v[174:177], v[230:233], v[104:107]
	v_mfma_f32_16x16x32_bf16 v[88:91], v[174:177], v[242:245], v[88:91]
	v_mfma_f32_16x16x32_bf16 v[84:87], v[182:185], v[242:245], v[84:87]
	v_mfma_f32_16x16x32_bf16 v[68:71], v[182:185], v[246:249], v[68:71]
	v_mfma_f32_16x16x32_bf16 v[72:75], v[174:177], v[246:249], v[72:75]
	s_barrier
	s_add_i32 s24, s1, s77
	v_lshl_add_u64 v[154:155], s[86:87], 0, v[158:159]
	s_mov_b32 m0, s24
	ds_read_b128 v[218:221], v207 offset:16384
	ds_read_b128 v[222:225], v207 offset:18432
	ds_read_b128 v[226:229], v208 offset:16384
	ds_read_b128 v[230:233], v208 offset:18432
	ds_read_b128 v[234:237], v207 offset:20480
	ds_read_b128 v[238:241], v207 offset:22528
	ds_read_b128 v[242:245], v208 offset:20480
	ds_read_b128 v[246:249], v208 offset:22528
	global_load_lds_dwordx4 v[154:155], off
	v_lshl_add_u64 v[250:251], v[154:155], 0, s[14:15]
	s_add_i32 m0, s24, 0x2000
	s_add_i32 s24, s12, s77
	global_load_lds_dwordx4 v[250:251], off
	v_lshl_add_u64 v[250:251], v[154:155], 0, s[16:17]
	s_mov_b32 m0, s24
	s_nop 0
	global_load_lds_dwordx4 v[250:251], off
	v_lshl_add_u64 v[250:251], v[154:155], 0, s[18:19]
	s_add_i32 m0, s24, 0x2000
	s_nop 0
	global_load_lds_dwordx4 v[250:251], off
	s_waitcnt vmcnt(4)
	s_waitcnt lgkmcnt(0)
	s_barrier
	v_mfma_f32_16x16x32_bf16 v[64:67], v[134:137], v[218:221], 0
	v_mfma_f32_16x16x32_bf16 v[60:63], v[142:145], v[218:221], 0
	v_mfma_f32_16x16x32_bf16 v[44:47], v[142:145], v[222:225], 0
	v_mfma_f32_16x16x32_bf16 v[48:51], v[134:137], v[222:225], 0
	v_mfma_f32_16x16x32_bf16 v[32:35], v[134:137], v[234:237], 0
	v_mfma_f32_16x16x32_bf16 v[28:31], v[142:145], v[234:237], 0
	v_mfma_f32_16x16x32_bf16 v[12:15], v[142:145], v[238:241], 0
	v_mfma_f32_16x16x32_bf16 v[16:19], v[134:137], v[238:241], 0
	v_mfma_f32_16x16x32_bf16 v[64:67], v[138:141], v[226:229], v[64:67]
	v_mfma_f32_16x16x32_bf16 v[60:63], v[146:149], v[226:229], v[60:63]
	v_mfma_f32_16x16x32_bf16 v[44:47], v[146:149], v[230:233], v[44:47]
	v_mfma_f32_16x16x32_bf16 v[48:51], v[138:141], v[230:233], v[48:51]
	v_mfma_f32_16x16x32_bf16 v[32:35], v[138:141], v[242:245], v[32:35]
	v_mfma_f32_16x16x32_bf16 v[28:31], v[146:149], v[242:245], v[28:31]
	v_mfma_f32_16x16x32_bf16 v[12:15], v[146:149], v[246:249], v[12:15]
	v_mfma_f32_16x16x32_bf16 v[16:19], v[138:141], v[246:249], v[16:19]
	v_mfma_f32_16x16x32_bf16 v[56:59], v[150:153], v[218:221], 0
	v_mfma_f32_16x16x32_bf16 v[52:55], v[178:181], v[218:221], 0
	v_mfma_f32_16x16x32_bf16 v[36:39], v[178:181], v[222:225], 0
	v_mfma_f32_16x16x32_bf16 v[40:43], v[150:153], v[222:225], 0
	v_mfma_f32_16x16x32_bf16 v[24:27], v[150:153], v[234:237], 0
	v_mfma_f32_16x16x32_bf16 v[20:23], v[178:181], v[234:237], 0
	v_mfma_f32_16x16x32_bf16 v[4:7], v[178:181], v[238:241], 0
	v_mfma_f32_16x16x32_bf16 v[8:11], v[150:153], v[238:241], 0
	v_mfma_f32_16x16x32_bf16 v[56:59], v[174:177], v[226:229], v[56:59]
	v_mfma_f32_16x16x32_bf16 v[52:55], v[182:185], v[226:229], v[52:55]
	v_mfma_f32_16x16x32_bf16 v[36:39], v[182:185], v[230:233], v[36:39]
	v_mfma_f32_16x16x32_bf16 v[40:43], v[174:177], v[230:233], v[40:43]
	v_mfma_f32_16x16x32_bf16 v[24:27], v[174:177], v[242:245], v[24:27]
	v_mfma_f32_16x16x32_bf16 v[20:23], v[182:185], v[242:245], v[20:23]
	v_mfma_f32_16x16x32_bf16 v[4:7], v[182:185], v[246:249], v[4:7]
	v_mfma_f32_16x16x32_bf16 v[8:11], v[174:177], v[246:249], v[8:11]
	s_barrier
	ds_read_b128 v[134:137], v213
	ds_read_b128 v[138:141], v214
	ds_read_b128 v[142:145], v209
	ds_read_b128 v[146:149], v210
	ds_read_b128 v[150:153], v215
	ds_read_b128 v[174:177], v216
	ds_read_b128 v[178:181], v211
	ds_read_b128 v[182:185], v212
	s_mov_b32 m0, s79
	v_lshl_add_u64 v[250:251], s[82:83], 0, v[0:1]
	ds_read_b128 v[218:221], v207 offset:32768
	ds_read_b128 v[222:225], v207 offset:34816
	ds_read_b128 v[226:229], v208 offset:32768
	ds_read_b128 v[230:233], v208 offset:34816
	ds_read_b128 v[234:237], v207 offset:36864
	ds_read_b128 v[238:241], v207 offset:38912
	ds_read_b128 v[242:245], v208 offset:36864
	ds_read_b128 v[246:249], v208 offset:38912
	global_load_lds_dwordx4 v[250:251], off
	v_lshl_add_u64 v[252:253], v[250:251], 0, s[20:21]
	s_mov_b32 m0, s81
	s_nop 0
	global_load_lds_dwordx4 v[252:253], off
	v_lshl_add_u64 v[252:253], v[250:251], 0, s[14:15]
	s_mov_b32 m0, s97
	v_lshl_add_u64 v[250:251], v[250:251], 0, s[22:23]
	global_load_lds_dwordx4 v[252:253], off
	s_mov_b32 m0, s64
	s_nop 0
	global_load_lds_dwordx4 v[250:251], off
	s_waitcnt vmcnt(8)
	s_waitcnt lgkmcnt(0)
	s_barrier
	v_mfma_f32_16x16x32_bf16 v[128:131], v[134:137], v[218:221], v[128:131]
	v_mfma_f32_16x16x32_bf16 v[124:127], v[142:145], v[218:221], v[124:127]
	v_mfma_f32_16x16x32_bf16 v[108:111], v[142:145], v[222:225], v[108:111]
	v_mfma_f32_16x16x32_bf16 v[112:115], v[134:137], v[222:225], v[112:115]
	v_mfma_f32_16x16x32_bf16 v[96:99], v[134:137], v[234:237], v[96:99]
	v_mfma_f32_16x16x32_bf16 v[92:95], v[142:145], v[234:237], v[92:95]
	v_mfma_f32_16x16x32_bf16 v[76:79], v[142:145], v[238:241], v[76:79]
	v_mfma_f32_16x16x32_bf16 v[80:83], v[134:137], v[238:241], v[80:83]
	v_mfma_f32_16x16x32_bf16 v[128:131], v[138:141], v[226:229], v[128:131]
	v_mfma_f32_16x16x32_bf16 v[124:127], v[146:149], v[226:229], v[124:127]
	v_mfma_f32_16x16x32_bf16 v[108:111], v[146:149], v[230:233], v[108:111]
	v_mfma_f32_16x16x32_bf16 v[112:115], v[138:141], v[230:233], v[112:115]
	v_mfma_f32_16x16x32_bf16 v[96:99], v[138:141], v[242:245], v[96:99]
	v_mfma_f32_16x16x32_bf16 v[92:95], v[146:149], v[242:245], v[92:95]
	v_mfma_f32_16x16x32_bf16 v[76:79], v[146:149], v[246:249], v[76:79]
	v_mfma_f32_16x16x32_bf16 v[80:83], v[138:141], v[246:249], v[80:83]
	v_mfma_f32_16x16x32_bf16 v[120:123], v[150:153], v[218:221], v[120:123]
	v_mfma_f32_16x16x32_bf16 v[116:119], v[178:181], v[218:221], v[116:119]
	v_mfma_f32_16x16x32_bf16 v[100:103], v[178:181], v[222:225], v[100:103]
	v_mfma_f32_16x16x32_bf16 v[104:107], v[150:153], v[222:225], v[104:107]
	v_mfma_f32_16x16x32_bf16 v[88:91], v[150:153], v[234:237], v[88:91]
	v_mfma_f32_16x16x32_bf16 v[84:87], v[178:181], v[234:237], v[84:87]
	v_mfma_f32_16x16x32_bf16 v[68:71], v[178:181], v[238:241], v[68:71]
	v_mfma_f32_16x16x32_bf16 v[72:75], v[150:153], v[238:241], v[72:75]
	v_mfma_f32_16x16x32_bf16 v[120:123], v[174:177], v[226:229], v[120:123]
	v_mfma_f32_16x16x32_bf16 v[116:119], v[182:185], v[226:229], v[116:119]
	v_mfma_f32_16x16x32_bf16 v[100:103], v[182:185], v[230:233], v[100:103]
	v_mfma_f32_16x16x32_bf16 v[104:107], v[174:177], v[230:233], v[104:107]
	v_mfma_f32_16x16x32_bf16 v[88:91], v[174:177], v[242:245], v[88:91]
	v_mfma_f32_16x16x32_bf16 v[84:87], v[182:185], v[242:245], v[84:87]
	v_mfma_f32_16x16x32_bf16 v[68:71], v[182:185], v[246:249], v[68:71]
	v_mfma_f32_16x16x32_bf16 v[72:75], v[174:177], v[246:249], v[72:75]
	s_barrier
	s_add_i32 s24, s70, s77
	v_lshl_add_u64 v[250:251], v[154:155], 0, s[48:49]
	s_mov_b32 m0, s24
	ds_read_b128 v[218:221], v207 offset:49152
	ds_read_b128 v[222:225], v207 offset:51200
	ds_read_b128 v[226:229], v208 offset:49152
	ds_read_b128 v[230:233], v208 offset:51200
	ds_read_b128 v[234:237], v207 offset:53248
	ds_read_b128 v[238:241], v207 offset:55296
	ds_read_b128 v[242:245], v208 offset:53248
	ds_read_b128 v[246:249], v208 offset:55296
	global_load_lds_dwordx4 v[250:251], off
	v_lshl_add_u64 v[250:251], v[154:155], 0, s[50:51]
	s_add_i32 m0, s24, 0x2000
	s_add_i32 s24, s71, s77
	global_load_lds_dwordx4 v[250:251], off
	v_lshl_add_u64 v[250:251], v[154:155], 0, s[52:53]
	s_mov_b32 m0, s24
	v_lshl_add_u64 v[154:155], v[154:155], 0, s[54:55]
	global_load_lds_dwordx4 v[250:251], off
	s_add_i32 m0, s24, 0x2000
	s_nop 0
	global_load_lds_dwordx4 v[154:155], off
	s_waitcnt vmcnt(4)
	s_waitcnt lgkmcnt(0)
	s_barrier
	v_mfma_f32_16x16x32_bf16 v[64:67], v[134:137], v[218:221], v[64:67]
	v_mfma_f32_16x16x32_bf16 v[60:63], v[142:145], v[218:221], v[60:63]
	v_mfma_f32_16x16x32_bf16 v[44:47], v[142:145], v[222:225], v[44:47]
	v_mfma_f32_16x16x32_bf16 v[48:51], v[134:137], v[222:225], v[48:51]
	v_mfma_f32_16x16x32_bf16 v[32:35], v[134:137], v[234:237], v[32:35]
	v_mfma_f32_16x16x32_bf16 v[28:31], v[142:145], v[234:237], v[28:31]
	v_mfma_f32_16x16x32_bf16 v[12:15], v[142:145], v[238:241], v[12:15]
	v_mfma_f32_16x16x32_bf16 v[16:19], v[134:137], v[238:241], v[16:19]
	v_mfma_f32_16x16x32_bf16 v[64:67], v[138:141], v[226:229], v[64:67]
	v_mfma_f32_16x16x32_bf16 v[60:63], v[146:149], v[226:229], v[60:63]
	v_mfma_f32_16x16x32_bf16 v[44:47], v[146:149], v[230:233], v[44:47]
	v_mfma_f32_16x16x32_bf16 v[48:51], v[138:141], v[230:233], v[48:51]
	v_mfma_f32_16x16x32_bf16 v[32:35], v[138:141], v[242:245], v[32:35]
	v_mfma_f32_16x16x32_bf16 v[28:31], v[146:149], v[242:245], v[28:31]
	v_mfma_f32_16x16x32_bf16 v[12:15], v[146:149], v[246:249], v[12:15]
	v_mfma_f32_16x16x32_bf16 v[16:19], v[138:141], v[246:249], v[16:19]
	v_mfma_f32_16x16x32_bf16 v[56:59], v[150:153], v[218:221], v[56:59]
	v_mfma_f32_16x16x32_bf16 v[52:55], v[178:181], v[218:221], v[52:55]
	v_mfma_f32_16x16x32_bf16 v[36:39], v[178:181], v[222:225], v[36:39]
	v_mfma_f32_16x16x32_bf16 v[40:43], v[150:153], v[222:225], v[40:43]
	v_mfma_f32_16x16x32_bf16 v[24:27], v[150:153], v[234:237], v[24:27]
	v_mfma_f32_16x16x32_bf16 v[20:23], v[178:181], v[234:237], v[20:23]
	v_mfma_f32_16x16x32_bf16 v[4:7], v[178:181], v[238:241], v[4:7]
	v_mfma_f32_16x16x32_bf16 v[8:11], v[150:153], v[238:241], v[8:11]
	v_mfma_f32_16x16x32_bf16 v[56:59], v[174:177], v[226:229], v[56:59]
	v_mfma_f32_16x16x32_bf16 v[52:55], v[182:185], v[226:229], v[52:55]
	v_mfma_f32_16x16x32_bf16 v[36:39], v[182:185], v[230:233], v[36:39]
	v_mfma_f32_16x16x32_bf16 v[40:43], v[174:177], v[230:233], v[40:43]
	v_mfma_f32_16x16x32_bf16 v[24:27], v[174:177], v[242:245], v[24:27]
	v_mfma_f32_16x16x32_bf16 v[20:23], v[182:185], v[242:245], v[20:23]
	v_mfma_f32_16x16x32_bf16 v[4:7], v[182:185], v[246:249], v[4:7]
	v_mfma_f32_16x16x32_bf16 v[8:11], v[174:177], v[246:249], v[8:11]
	s_barrier
	s_add_i32 s94, s94, 2
	s_add_u32 vcc_lo, vcc_lo, 0x100
	s_addc_u32 vcc_hi, vcc_hi, 0
	s_cmp_gt_u32 s94, 13
.LBB0_384:
	ds_read_b128 v[134:137], v199
	ds_read_b128 v[138:141], v200
	ds_read_b128 v[142:145], v201
	ds_read_b128 v[146:149], v202
	ds_read_b128 v[150:153], v203
	ds_read_b128 v[174:177], v204
	ds_read_b128 v[178:181], v205
	ds_read_b128 v[182:185], v206
	s_add_u32 s24, s4, vcc_lo
	s_addc_u32 s25, s5, vcc_hi
	s_add_u32 s24, s24, 0x100
	s_addc_u32 s25, s25, 0
	s_add_u32 s82, s39, vcc_lo
	s_addc_u32 s83, s67, vcc_hi
	s_cmpk_eq_i32 vcc_lo, 0x700
	s_cselect_b32 s87, s29, s83
	s_cselect_b32 s86, s38, s82
	s_cselect_b32 s83, s34, s25
	s_cselect_b32 s82, s35, s24
	v_lshl_add_u64 v[154:155], v[132:133], 0, vcc
	v_lshl_add_u64 v[250:251], v[154:155], 0, s[48:49]
	s_add_i32 m0, s79, 0x8000
	s_mov_b64 s[24:25], 0x20080
	ds_read_b128 v[218:221], v207
	ds_read_b128 v[222:225], v207 offset:2048
	ds_read_b128 v[226:229], v208
	ds_read_b128 v[230:233], v208 offset:2048
	ds_read_b128 v[234:237], v207 offset:4096
	ds_read_b128 v[238:241], v207 offset:6144
	ds_read_b128 v[242:245], v208 offset:4096
	ds_read_b128 v[246:249], v208 offset:6144
	global_load_lds_dwordx4 v[250:251], off
	v_lshl_add_u64 v[250:251], v[154:155], 0, s[24:25]
	s_add_i32 m0, s79, 0xa000
	s_mov_b64 s[24:25], 0x60080
	global_load_lds_dwordx4 v[250:251], off
	v_lshl_add_u64 v[250:251], v[154:155], 0, s[50:51]
	s_add_i32 m0, s79, 0xc000
	v_lshl_add_u64 v[154:155], v[154:155], 0, s[24:25]
	global_load_lds_dwordx4 v[250:251], off
	s_add_i32 m0, s79, 0xe000
	s_nop 0
	global_load_lds_dwordx4 v[154:155], off
	s_waitcnt vmcnt(8)
	s_waitcnt lgkmcnt(0)
	s_barrier
	v_mfma_f32_16x16x32_bf16 v[128:131], v[134:137], v[218:221], v[128:131]
	v_mfma_f32_16x16x32_bf16 v[124:127], v[142:145], v[218:221], v[124:127]
	v_mfma_f32_16x16x32_bf16 v[108:111], v[142:145], v[222:225], v[108:111]
	v_mfma_f32_16x16x32_bf16 v[112:115], v[134:137], v[222:225], v[112:115]
	v_mfma_f32_16x16x32_bf16 v[96:99], v[134:137], v[234:237], v[96:99]
	v_mfma_f32_16x16x32_bf16 v[92:95], v[142:145], v[234:237], v[92:95]
	v_mfma_f32_16x16x32_bf16 v[76:79], v[142:145], v[238:241], v[76:79]
	v_mfma_f32_16x16x32_bf16 v[80:83], v[134:137], v[238:241], v[80:83]
	v_mfma_f32_16x16x32_bf16 v[128:131], v[138:141], v[226:229], v[128:131]
	v_mfma_f32_16x16x32_bf16 v[124:127], v[146:149], v[226:229], v[124:127]
	v_mfma_f32_16x16x32_bf16 v[108:111], v[146:149], v[230:233], v[108:111]
	v_mfma_f32_16x16x32_bf16 v[112:115], v[138:141], v[230:233], v[112:115]
	v_mfma_f32_16x16x32_bf16 v[96:99], v[138:141], v[242:245], v[96:99]
	v_mfma_f32_16x16x32_bf16 v[92:95], v[146:149], v[242:245], v[92:95]
	v_mfma_f32_16x16x32_bf16 v[76:79], v[146:149], v[246:249], v[76:79]
	v_mfma_f32_16x16x32_bf16 v[80:83], v[138:141], v[246:249], v[80:83]
	v_mfma_f32_16x16x32_bf16 v[120:123], v[150:153], v[218:221], v[120:123]
	v_mfma_f32_16x16x32_bf16 v[116:119], v[178:181], v[218:221], v[116:119]
	v_mfma_f32_16x16x32_bf16 v[100:103], v[178:181], v[222:225], v[100:103]
	v_mfma_f32_16x16x32_bf16 v[104:107], v[150:153], v[222:225], v[104:107]
	v_mfma_f32_16x16x32_bf16 v[88:91], v[150:153], v[234:237], v[88:91]
	v_mfma_f32_16x16x32_bf16 v[84:87], v[178:181], v[234:237], v[84:87]
	v_mfma_f32_16x16x32_bf16 v[68:71], v[178:181], v[238:241], v[68:71]
	v_mfma_f32_16x16x32_bf16 v[72:75], v[150:153], v[238:241], v[72:75]
	v_mfma_f32_16x16x32_bf16 v[120:123], v[174:177], v[226:229], v[120:123]
	v_mfma_f32_16x16x32_bf16 v[116:119], v[182:185], v[226:229], v[116:119]
	v_mfma_f32_16x16x32_bf16 v[100:103], v[182:185], v[230:233], v[100:103]
	v_mfma_f32_16x16x32_bf16 v[104:107], v[174:177], v[230:233], v[104:107]
	v_mfma_f32_16x16x32_bf16 v[88:91], v[174:177], v[242:245], v[88:91]
	v_mfma_f32_16x16x32_bf16 v[84:87], v[182:185], v[242:245], v[84:87]
	v_mfma_f32_16x16x32_bf16 v[68:71], v[182:185], v[246:249], v[68:71]
	v_mfma_f32_16x16x32_bf16 v[72:75], v[174:177], v[246:249], v[72:75]
	s_barrier
	s_add_i32 s24, s1, s77
	v_lshl_add_u64 v[154:155], s[86:87], 0, v[158:159]
	s_mov_b32 m0, s24
	ds_read_b128 v[218:221], v207 offset:16384
	ds_read_b128 v[222:225], v207 offset:18432
	ds_read_b128 v[226:229], v208 offset:16384
	ds_read_b128 v[230:233], v208 offset:18432
	ds_read_b128 v[234:237], v207 offset:20480
	ds_read_b128 v[238:241], v207 offset:22528
	ds_read_b128 v[242:245], v208 offset:20480
	ds_read_b128 v[246:249], v208 offset:22528
	global_load_lds_dwordx4 v[154:155], off
	v_lshl_add_u64 v[250:251], v[154:155], 0, s[14:15]
	s_add_i32 m0, s24, 0x2000
	s_add_i32 s24, s12, s77
	global_load_lds_dwordx4 v[250:251], off
	v_lshl_add_u64 v[250:251], v[154:155], 0, s[16:17]
	s_mov_b32 m0, s24
	s_nop 0
	global_load_lds_dwordx4 v[250:251], off
	v_lshl_add_u64 v[250:251], v[154:155], 0, s[18:19]
	s_add_i32 m0, s24, 0x2000
	s_nop 0
	global_load_lds_dwordx4 v[250:251], off
	s_waitcnt vmcnt(4)
	s_waitcnt lgkmcnt(0)
	s_barrier
	v_mfma_f32_16x16x32_bf16 v[64:67], v[134:137], v[218:221], v[64:67]
	v_mfma_f32_16x16x32_bf16 v[60:63], v[142:145], v[218:221], v[60:63]
	v_mfma_f32_16x16x32_bf16 v[44:47], v[142:145], v[222:225], v[44:47]
	v_mfma_f32_16x16x32_bf16 v[48:51], v[134:137], v[222:225], v[48:51]
	v_mfma_f32_16x16x32_bf16 v[32:35], v[134:137], v[234:237], v[32:35]
	v_mfma_f32_16x16x32_bf16 v[28:31], v[142:145], v[234:237], v[28:31]
	v_mfma_f32_16x16x32_bf16 v[12:15], v[142:145], v[238:241], v[12:15]
	v_mfma_f32_16x16x32_bf16 v[16:19], v[134:137], v[238:241], v[16:19]
	v_mfma_f32_16x16x32_bf16 v[64:67], v[138:141], v[226:229], v[64:67]
	v_mfma_f32_16x16x32_bf16 v[60:63], v[146:149], v[226:229], v[60:63]
	v_mfma_f32_16x16x32_bf16 v[44:47], v[146:149], v[230:233], v[44:47]
	v_mfma_f32_16x16x32_bf16 v[48:51], v[138:141], v[230:233], v[48:51]
	v_mfma_f32_16x16x32_bf16 v[32:35], v[138:141], v[242:245], v[32:35]
	v_mfma_f32_16x16x32_bf16 v[28:31], v[146:149], v[242:245], v[28:31]
	v_mfma_f32_16x16x32_bf16 v[12:15], v[146:149], v[246:249], v[12:15]
	v_mfma_f32_16x16x32_bf16 v[16:19], v[138:141], v[246:249], v[16:19]
	v_mfma_f32_16x16x32_bf16 v[56:59], v[150:153], v[218:221], v[56:59]
	v_mfma_f32_16x16x32_bf16 v[52:55], v[178:181], v[218:221], v[52:55]
	v_mfma_f32_16x16x32_bf16 v[36:39], v[178:181], v[222:225], v[36:39]
	v_mfma_f32_16x16x32_bf16 v[40:43], v[150:153], v[222:225], v[40:43]
	v_mfma_f32_16x16x32_bf16 v[24:27], v[150:153], v[234:237], v[24:27]
	v_mfma_f32_16x16x32_bf16 v[20:23], v[178:181], v[234:237], v[20:23]
	v_mfma_f32_16x16x32_bf16 v[4:7], v[178:181], v[238:241], v[4:7]
	v_mfma_f32_16x16x32_bf16 v[8:11], v[150:153], v[238:241], v[8:11]
	v_mfma_f32_16x16x32_bf16 v[56:59], v[174:177], v[226:229], v[56:59]
	v_mfma_f32_16x16x32_bf16 v[52:55], v[182:185], v[226:229], v[52:55]
	v_mfma_f32_16x16x32_bf16 v[36:39], v[182:185], v[230:233], v[36:39]
	v_mfma_f32_16x16x32_bf16 v[40:43], v[174:177], v[230:233], v[40:43]
	v_mfma_f32_16x16x32_bf16 v[24:27], v[174:177], v[242:245], v[24:27]
	v_mfma_f32_16x16x32_bf16 v[20:23], v[182:185], v[242:245], v[20:23]
	v_mfma_f32_16x16x32_bf16 v[4:7], v[182:185], v[246:249], v[4:7]
	v_mfma_f32_16x16x32_bf16 v[8:11], v[174:177], v[246:249], v[8:11]
	s_barrier
	ds_read_b128 v[134:137], v213
	ds_read_b128 v[138:141], v214
	ds_read_b128 v[142:145], v209
	ds_read_b128 v[146:149], v210
	ds_read_b128 v[150:153], v215
	ds_read_b128 v[174:177], v216
	ds_read_b128 v[178:181], v211
	ds_read_b128 v[182:185], v212
	s_mov_b32 m0, s79
	v_lshl_add_u64 v[250:251], s[82:83], 0, v[0:1]
	ds_read_b128 v[218:221], v207 offset:32768
	ds_read_b128 v[222:225], v207 offset:34816
	ds_read_b128 v[226:229], v208 offset:32768
	ds_read_b128 v[230:233], v208 offset:34816
	ds_read_b128 v[234:237], v207 offset:36864
	ds_read_b128 v[238:241], v207 offset:38912
	ds_read_b128 v[242:245], v208 offset:36864
	ds_read_b128 v[246:249], v208 offset:38912
	global_load_lds_dwordx4 v[250:251], off
	v_lshl_add_u64 v[252:253], v[250:251], 0, s[20:21]
	s_mov_b32 m0, s81
	s_nop 0
	global_load_lds_dwordx4 v[252:253], off
	v_lshl_add_u64 v[252:253], v[250:251], 0, s[14:15]
	s_mov_b32 m0, s97
	v_lshl_add_u64 v[250:251], v[250:251], 0, s[22:23]
	global_load_lds_dwordx4 v[252:253], off
	s_mov_b32 m0, s64
	s_nop 0
	global_load_lds_dwordx4 v[250:251], off
	s_waitcnt vmcnt(8)
	s_waitcnt lgkmcnt(0)
	s_barrier
	v_mfma_f32_16x16x32_bf16 v[128:131], v[134:137], v[218:221], v[128:131]
	v_mfma_f32_16x16x32_bf16 v[124:127], v[142:145], v[218:221], v[124:127]
	v_mfma_f32_16x16x32_bf16 v[108:111], v[142:145], v[222:225], v[108:111]
	v_mfma_f32_16x16x32_bf16 v[112:115], v[134:137], v[222:225], v[112:115]
	v_mfma_f32_16x16x32_bf16 v[96:99], v[134:137], v[234:237], v[96:99]
	v_mfma_f32_16x16x32_bf16 v[92:95], v[142:145], v[234:237], v[92:95]
	v_mfma_f32_16x16x32_bf16 v[76:79], v[142:145], v[238:241], v[76:79]
	v_mfma_f32_16x16x32_bf16 v[80:83], v[134:137], v[238:241], v[80:83]
	v_mfma_f32_16x16x32_bf16 v[128:131], v[138:141], v[226:229], v[128:131]
	v_mfma_f32_16x16x32_bf16 v[124:127], v[146:149], v[226:229], v[124:127]
	v_mfma_f32_16x16x32_bf16 v[108:111], v[146:149], v[230:233], v[108:111]
	v_mfma_f32_16x16x32_bf16 v[112:115], v[138:141], v[230:233], v[112:115]
	v_mfma_f32_16x16x32_bf16 v[96:99], v[138:141], v[242:245], v[96:99]
	v_mfma_f32_16x16x32_bf16 v[92:95], v[146:149], v[242:245], v[92:95]
	v_mfma_f32_16x16x32_bf16 v[76:79], v[146:149], v[246:249], v[76:79]
	v_mfma_f32_16x16x32_bf16 v[80:83], v[138:141], v[246:249], v[80:83]
	v_mfma_f32_16x16x32_bf16 v[120:123], v[150:153], v[218:221], v[120:123]
	v_mfma_f32_16x16x32_bf16 v[116:119], v[178:181], v[218:221], v[116:119]
	v_mfma_f32_16x16x32_bf16 v[100:103], v[178:181], v[222:225], v[100:103]
	v_mfma_f32_16x16x32_bf16 v[104:107], v[150:153], v[222:225], v[104:107]
	v_mfma_f32_16x16x32_bf16 v[88:91], v[150:153], v[234:237], v[88:91]
	v_mfma_f32_16x16x32_bf16 v[84:87], v[178:181], v[234:237], v[84:87]
	v_mfma_f32_16x16x32_bf16 v[68:71], v[178:181], v[238:241], v[68:71]
	v_mfma_f32_16x16x32_bf16 v[72:75], v[150:153], v[238:241], v[72:75]
	v_mfma_f32_16x16x32_bf16 v[120:123], v[174:177], v[226:229], v[120:123]
	v_mfma_f32_16x16x32_bf16 v[116:119], v[182:185], v[226:229], v[116:119]
	v_mfma_f32_16x16x32_bf16 v[100:103], v[182:185], v[230:233], v[100:103]
	v_mfma_f32_16x16x32_bf16 v[104:107], v[174:177], v[230:233], v[104:107]
	v_mfma_f32_16x16x32_bf16 v[88:91], v[174:177], v[242:245], v[88:91]
	v_mfma_f32_16x16x32_bf16 v[84:87], v[182:185], v[242:245], v[84:87]
	v_mfma_f32_16x16x32_bf16 v[68:71], v[182:185], v[246:249], v[68:71]
	v_mfma_f32_16x16x32_bf16 v[72:75], v[174:177], v[246:249], v[72:75]
	s_barrier
	s_add_i32 s24, s70, s77
	v_lshl_add_u64 v[250:251], v[154:155], 0, s[48:49]
	s_mov_b32 m0, s24
	ds_read_b128 v[218:221], v207 offset:49152
	ds_read_b128 v[222:225], v207 offset:51200
	ds_read_b128 v[226:229], v208 offset:49152
	ds_read_b128 v[230:233], v208 offset:51200
	ds_read_b128 v[234:237], v207 offset:53248
	ds_read_b128 v[238:241], v207 offset:55296
	ds_read_b128 v[242:245], v208 offset:53248
	ds_read_b128 v[246:249], v208 offset:55296
	global_load_lds_dwordx4 v[250:251], off
	v_lshl_add_u64 v[250:251], v[154:155], 0, s[50:51]
	s_add_i32 m0, s24, 0x2000
	s_add_i32 s24, s71, s77
	global_load_lds_dwordx4 v[250:251], off
	v_lshl_add_u64 v[250:251], v[154:155], 0, s[52:53]
	s_mov_b32 m0, s24
	v_lshl_add_u64 v[154:155], v[154:155], 0, s[54:55]
	global_load_lds_dwordx4 v[250:251], off
	s_add_i32 m0, s24, 0x2000
	s_nop 0
	global_load_lds_dwordx4 v[154:155], off
	s_waitcnt vmcnt(4)
	s_waitcnt lgkmcnt(0)
	s_barrier
	v_mfma_f32_16x16x32_bf16 v[64:67], v[134:137], v[218:221], v[64:67]
	v_mfma_f32_16x16x32_bf16 v[60:63], v[142:145], v[218:221], v[60:63]
	v_mfma_f32_16x16x32_bf16 v[44:47], v[142:145], v[222:225], v[44:47]
	v_mfma_f32_16x16x32_bf16 v[48:51], v[134:137], v[222:225], v[48:51]
	v_mfma_f32_16x16x32_bf16 v[32:35], v[134:137], v[234:237], v[32:35]
	v_mfma_f32_16x16x32_bf16 v[28:31], v[142:145], v[234:237], v[28:31]
	v_mfma_f32_16x16x32_bf16 v[12:15], v[142:145], v[238:241], v[12:15]
	v_mfma_f32_16x16x32_bf16 v[16:19], v[134:137], v[238:241], v[16:19]
	v_mfma_f32_16x16x32_bf16 v[64:67], v[138:141], v[226:229], v[64:67]
	v_mfma_f32_16x16x32_bf16 v[60:63], v[146:149], v[226:229], v[60:63]
	v_mfma_f32_16x16x32_bf16 v[44:47], v[146:149], v[230:233], v[44:47]
	v_mfma_f32_16x16x32_bf16 v[48:51], v[138:141], v[230:233], v[48:51]
	v_mfma_f32_16x16x32_bf16 v[32:35], v[138:141], v[242:245], v[32:35]
	v_mfma_f32_16x16x32_bf16 v[28:31], v[146:149], v[242:245], v[28:31]
	v_mfma_f32_16x16x32_bf16 v[12:15], v[146:149], v[246:249], v[12:15]
	v_mfma_f32_16x16x32_bf16 v[16:19], v[138:141], v[246:249], v[16:19]
	v_mfma_f32_16x16x32_bf16 v[56:59], v[150:153], v[218:221], v[56:59]
	v_mfma_f32_16x16x32_bf16 v[52:55], v[178:181], v[218:221], v[52:55]
	v_mfma_f32_16x16x32_bf16 v[36:39], v[178:181], v[222:225], v[36:39]
	v_mfma_f32_16x16x32_bf16 v[40:43], v[150:153], v[222:225], v[40:43]
	v_mfma_f32_16x16x32_bf16 v[24:27], v[150:153], v[234:237], v[24:27]
	v_mfma_f32_16x16x32_bf16 v[20:23], v[178:181], v[234:237], v[20:23]
	v_mfma_f32_16x16x32_bf16 v[4:7], v[178:181], v[238:241], v[4:7]
	v_mfma_f32_16x16x32_bf16 v[8:11], v[150:153], v[238:241], v[8:11]
	v_mfma_f32_16x16x32_bf16 v[56:59], v[174:177], v[226:229], v[56:59]
	v_mfma_f32_16x16x32_bf16 v[52:55], v[182:185], v[226:229], v[52:55]
	v_mfma_f32_16x16x32_bf16 v[36:39], v[182:185], v[230:233], v[36:39]
	v_mfma_f32_16x16x32_bf16 v[40:43], v[174:177], v[230:233], v[40:43]
	v_mfma_f32_16x16x32_bf16 v[24:27], v[174:177], v[242:245], v[24:27]
	v_mfma_f32_16x16x32_bf16 v[20:23], v[182:185], v[242:245], v[20:23]
	v_mfma_f32_16x16x32_bf16 v[4:7], v[182:185], v[246:249], v[4:7]
	v_mfma_f32_16x16x32_bf16 v[8:11], v[174:177], v[246:249], v[8:11]
	s_barrier
	s_add_i32 s94, s94, 2
	s_add_u32 vcc_lo, vcc_lo, 0x100
	s_addc_u32 vcc_hi, vcc_hi, 0
	s_cmp_gt_u32 s94, 13
	s_cbranch_scc0 .LBB0_384
	s_and_b64 vcc, exec, s[56:57]
	s_cbranch_vccz .LBB0_387
	s_barrier

.LBB0_779:
	v_add_u32_e32 v4, s73, v159
	v_add_u32_e32 v6, s73, v173
	ds_read_b128 v[136:139], v4
	ds_read_b128 v[140:143], v6
	v_add_u32_e32 v4, s77, v159
	s_add_u32 s26, s28, s64
	v_add_u32_e32 v6, s77, v173
	ds_read_b128 v[180:183], v4
	ds_read_b128 v[196:199], v6
	v_add_u32_e32 v4, s79, v159
	s_addc_u32 s27, s29, s65
	v_add_u32_e32 v6, s79, v173
	ds_read_b128 v[200:203], v4
	ds_read_b128 v[204:207], v6
	v_add_u32_e32 v4, s80, v159
	s_add_u32 s26, s26, 0x100
	v_add_u32_e32 v6, s80, v173
	ds_read_b128 v[208:211], v4
	ds_read_b128 v[212:215], v6
	s_addc_u32 s27, s27, 0
	s_add_u32 s34, s93, s64
	s_addc_u32 s35, s94, s65
	s_cmpk_eq_i32 s64, 0xb00
	s_cselect_b32 s35, s63, s35
	s_cselect_b32 s34, s62, s34
	s_cselect_b32 s27, s1, s27
	s_cselect_b32 s26, s0, s26
	v_lshl_add_u64 v[6:7], v[170:171], 0, s[64:65]
	v_lshl_add_u64 v[184:185], v[6:7], 0, s[24:25]
	s_add_i32 m0, s66, 0x8000
	s_mov_b64 s[38:39], 0x30080
	ds_read_b128 v[216:219], v176
	ds_read_b128 v[220:223], v176 offset:2048
	ds_read_b128 v[224:227], v177
	ds_read_b128 v[228:231], v177 offset:2048
	ds_read_b128 v[232:235], v176 offset:4096
	ds_read_b128 v[236:239], v176 offset:6144
	ds_read_b128 v[240:243], v177 offset:4096
	ds_read_b128 v[244:247], v177 offset:6144
	global_load_lds_dwordx4 v[184:185], off
	v_lshl_add_u64 v[184:185], v[6:7], 0, s[38:39]
	s_add_i32 m0, s66, 0xa000
	s_mov_b64 s[38:39], 0x90080
	global_load_lds_dwordx4 v[184:185], off
	v_lshl_add_u64 v[184:185], v[6:7], 0, s[50:51]
	s_add_i32 m0, s66, 0xc000
	v_lshl_add_u64 v[6:7], v[6:7], 0, s[38:39]
	global_load_lds_dwordx4 v[184:185], off
	s_add_i32 m0, s66, 0xe000
	s_nop 0
	global_load_lds_dwordx4 v[6:7], off
	s_waitcnt vmcnt(8)
	s_waitcnt lgkmcnt(0)
	s_barrier
	v_mfma_f32_16x16x32_bf16 v[132:135], v[136:139], v[216:219], v[132:135]
	v_mfma_f32_16x16x32_bf16 v[128:131], v[180:183], v[216:219], v[128:131]
	v_mfma_f32_16x16x32_bf16 v[112:115], v[180:183], v[220:223], v[112:115]
	v_mfma_f32_16x16x32_bf16 v[116:119], v[136:139], v[220:223], v[116:119]
	v_mfma_f32_16x16x32_bf16 v[100:103], v[136:139], v[232:235], v[100:103]
	v_mfma_f32_16x16x32_bf16 v[96:99], v[180:183], v[232:235], v[96:99]
	v_mfma_f32_16x16x32_bf16 v[80:83], v[180:183], v[236:239], v[80:83]
	v_mfma_f32_16x16x32_bf16 v[84:87], v[136:139], v[236:239], v[84:87]
	v_mfma_f32_16x16x32_bf16 v[132:135], v[140:143], v[224:227], v[132:135]
	v_mfma_f32_16x16x32_bf16 v[128:131], v[196:199], v[224:227], v[128:131]
	v_mfma_f32_16x16x32_bf16 v[112:115], v[196:199], v[228:231], v[112:115]
	v_mfma_f32_16x16x32_bf16 v[116:119], v[140:143], v[228:231], v[116:119]
	v_mfma_f32_16x16x32_bf16 v[100:103], v[140:143], v[240:243], v[100:103]
	v_mfma_f32_16x16x32_bf16 v[96:99], v[196:199], v[240:243], v[96:99]
	v_mfma_f32_16x16x32_bf16 v[80:83], v[196:199], v[244:247], v[80:83]
	v_mfma_f32_16x16x32_bf16 v[84:87], v[140:143], v[244:247], v[84:87]
	v_mfma_f32_16x16x32_bf16 v[124:127], v[200:203], v[216:219], v[124:127]
	v_mfma_f32_16x16x32_bf16 v[120:123], v[208:211], v[216:219], v[120:123]
	v_mfma_f32_16x16x32_bf16 v[104:107], v[208:211], v[220:223], v[104:107]
	v_mfma_f32_16x16x32_bf16 v[108:111], v[200:203], v[220:223], v[108:111]
	v_mfma_f32_16x16x32_bf16 v[92:95], v[200:203], v[232:235], v[92:95]
	v_mfma_f32_16x16x32_bf16 v[88:91], v[208:211], v[232:235], v[88:91]
	v_mfma_f32_16x16x32_bf16 v[72:75], v[208:211], v[236:239], v[72:75]
	v_mfma_f32_16x16x32_bf16 v[76:79], v[200:203], v[236:239], v[76:79]
	v_mfma_f32_16x16x32_bf16 v[124:127], v[204:207], v[224:227], v[124:127]
	v_mfma_f32_16x16x32_bf16 v[120:123], v[212:215], v[224:227], v[120:123]
	v_mfma_f32_16x16x32_bf16 v[104:107], v[212:215], v[228:231], v[104:107]
	v_mfma_f32_16x16x32_bf16 v[108:111], v[204:207], v[228:231], v[108:111]
	v_mfma_f32_16x16x32_bf16 v[92:95], v[204:207], v[240:243], v[92:95]
	v_mfma_f32_16x16x32_bf16 v[88:91], v[212:215], v[240:243], v[88:91]
	v_mfma_f32_16x16x32_bf16 v[72:75], v[212:215], v[244:247], v[72:75]
	v_mfma_f32_16x16x32_bf16 v[76:79], v[204:207], v[244:247], v[76:79]
	s_barrier
	v_lshl_add_u64 v[184:185], s[34:35], 0, v[146:147]
	s_add_i32 s34, s73, s3
	s_mov_b32 m0, s34
	ds_read_b128 v[216:219], v176 offset:16384
	ds_read_b128 v[220:223], v176 offset:18432
	ds_read_b128 v[224:227], v177 offset:16384
	ds_read_b128 v[228:231], v177 offset:18432
	ds_read_b128 v[232:235], v176 offset:20480
	ds_read_b128 v[236:239], v176 offset:22528
	ds_read_b128 v[240:243], v177 offset:20480
	ds_read_b128 v[244:247], v177 offset:22528
	global_load_lds_dwordx4 v[184:185], off
	v_lshl_add_u64 v[6:7], v[184:185], 0, s[12:13]
	s_add_i32 m0, s34, 0x2000
	s_add_i32 s34, s79, s3
	global_load_lds_dwordx4 v[6:7], off
	v_lshl_add_u64 v[6:7], v[184:185], 0, s[14:15]
	s_mov_b32 m0, s34
	s_nop 0
	global_load_lds_dwordx4 v[6:7], off
	v_lshl_add_u64 v[6:7], v[184:185], 0, s[16:17]
	s_add_i32 m0, s34, 0x2000
	s_nop 0
	global_load_lds_dwordx4 v[6:7], off
	s_waitcnt vmcnt(4)
	s_waitcnt lgkmcnt(0)
	s_barrier
	v_mfma_f32_16x16x32_bf16 v[68:71], v[136:139], v[216:219], v[68:71]
	v_mfma_f32_16x16x32_bf16 v[64:67], v[180:183], v[216:219], v[64:67]
	v_mfma_f32_16x16x32_bf16 v[48:51], v[180:183], v[220:223], v[48:51]
	v_mfma_f32_16x16x32_bf16 v[52:55], v[136:139], v[220:223], v[52:55]
	v_mfma_f32_16x16x32_bf16 v[36:39], v[136:139], v[232:235], v[36:39]
	v_mfma_f32_16x16x32_bf16 v[32:35], v[180:183], v[232:235], v[32:35]
	v_mfma_f32_16x16x32_bf16 v[16:19], v[180:183], v[236:239], v[16:19]
	v_mfma_f32_16x16x32_bf16 v[20:23], v[136:139], v[236:239], v[20:23]
	v_mfma_f32_16x16x32_bf16 v[68:71], v[140:143], v[224:227], v[68:71]
	v_mfma_f32_16x16x32_bf16 v[64:67], v[196:199], v[224:227], v[64:67]
	v_mfma_f32_16x16x32_bf16 v[48:51], v[196:199], v[228:231], v[48:51]
	v_mfma_f32_16x16x32_bf16 v[52:55], v[140:143], v[228:231], v[52:55]
	v_mfma_f32_16x16x32_bf16 v[36:39], v[140:143], v[240:243], v[36:39]
	v_mfma_f32_16x16x32_bf16 v[32:35], v[196:199], v[240:243], v[32:35]
	v_mfma_f32_16x16x32_bf16 v[16:19], v[196:199], v[244:247], v[16:19]
	v_mfma_f32_16x16x32_bf16 v[20:23], v[140:143], v[244:247], v[20:23]
	v_mfma_f32_16x16x32_bf16 v[60:63], v[200:203], v[216:219], v[60:63]
	v_mfma_f32_16x16x32_bf16 v[56:59], v[208:211], v[216:219], v[56:59]
	v_mfma_f32_16x16x32_bf16 v[40:43], v[208:211], v[220:223], v[40:43]
	v_mfma_f32_16x16x32_bf16 v[44:47], v[200:203], v[220:223], v[44:47]
	v_mfma_f32_16x16x32_bf16 v[28:31], v[200:203], v[232:235], v[28:31]
	v_mfma_f32_16x16x32_bf16 v[24:27], v[208:211], v[232:235], v[24:27]
	v_mfma_f32_16x16x32_bf16 v[6:9], v[208:211], v[236:239], v[8:11]
	v_mfma_f32_16x16x32_bf16 v[12:15], v[200:203], v[236:239], v[12:15]
	v_mfma_f32_16x16x32_bf16 v[60:63], v[204:207], v[224:227], v[60:63]
	v_mfma_f32_16x16x32_bf16 v[56:59], v[212:215], v[224:227], v[56:59]
	v_mfma_f32_16x16x32_bf16 v[40:43], v[212:215], v[228:231], v[40:43]
	v_mfma_f32_16x16x32_bf16 v[44:47], v[204:207], v[228:231], v[44:47]
	v_mfma_f32_16x16x32_bf16 v[28:31], v[204:207], v[240:243], v[28:31]
	v_mfma_f32_16x16x32_bf16 v[24:27], v[212:215], v[240:243], v[24:27]
	v_mfma_f32_16x16x32_bf16 v[6:9], v[212:215], v[244:247], v[6:9]
	v_mfma_f32_16x16x32_bf16 v[12:15], v[204:207], v[244:247], v[12:15]
	s_barrier
	v_add_u32_e32 v4, s83, v159
	v_add_u32_e32 v10, s83, v173
	ds_read_b128 v[136:139], v4
	ds_read_b128 v[140:143], v10
	v_add_u32_e32 v4, s81, v159
	v_add_u32_e32 v10, s81, v173
	ds_read_b128 v[180:183], v4
	ds_read_b128 v[196:199], v10
	v_add_u32_e32 v4, s84, v159
	v_add_u32_e32 v10, s84, v173
	ds_read_b128 v[200:203], v4
	ds_read_b128 v[204:207], v10
	v_add_u32_e32 v4, s82, v159
	v_add_u32_e32 v10, s82, v173
	ds_read_b128 v[208:211], v4
	ds_read_b128 v[212:215], v10
	s_mov_b32 m0, s66
	v_lshl_add_u64 v[10:11], s[26:27], 0, v[144:145]
	ds_read_b128 v[216:219], v176 offset:32768
	ds_read_b128 v[220:223], v176 offset:34816
	ds_read_b128 v[224:227], v177 offset:32768
	ds_read_b128 v[228:231], v177 offset:34816
	ds_read_b128 v[232:235], v176 offset:36864
	ds_read_b128 v[236:239], v176 offset:38912
	ds_read_b128 v[240:243], v177 offset:36864
	ds_read_b128 v[244:247], v177 offset:38912
	global_load_lds_dwordx4 v[10:11], off
	v_lshl_add_u64 v[248:249], v[10:11], 0, s[18:19]
	s_mov_b32 m0, s67
	s_nop 0
	global_load_lds_dwordx4 v[248:249], off
	v_lshl_add_u64 v[248:249], v[10:11], 0, s[12:13]
	s_mov_b32 m0, s68
	v_lshl_add_u64 v[10:11], v[10:11], 0, s[20:21]
	global_load_lds_dwordx4 v[248:249], off
	s_mov_b32 m0, s69
	s_nop 0
	global_load_lds_dwordx4 v[10:11], off
	s_waitcnt vmcnt(8)
	s_waitcnt lgkmcnt(0)
	s_barrier
	v_mfma_f32_16x16x32_bf16 v[132:135], v[136:139], v[216:219], v[132:135]
	v_mfma_f32_16x16x32_bf16 v[128:131], v[180:183], v[216:219], v[128:131]
	v_mfma_f32_16x16x32_bf16 v[112:115], v[180:183], v[220:223], v[112:115]
	v_mfma_f32_16x16x32_bf16 v[116:119], v[136:139], v[220:223], v[116:119]
	v_mfma_f32_16x16x32_bf16 v[100:103], v[136:139], v[232:235], v[100:103]
	v_mfma_f32_16x16x32_bf16 v[96:99], v[180:183], v[232:235], v[96:99]
	v_mfma_f32_16x16x32_bf16 v[80:83], v[180:183], v[236:239], v[80:83]
	v_mfma_f32_16x16x32_bf16 v[84:87], v[136:139], v[236:239], v[84:87]
	v_mfma_f32_16x16x32_bf16 v[132:135], v[140:143], v[224:227], v[132:135]
	v_mfma_f32_16x16x32_bf16 v[128:131], v[196:199], v[224:227], v[128:131]
	v_mfma_f32_16x16x32_bf16 v[112:115], v[196:199], v[228:231], v[112:115]
	v_mfma_f32_16x16x32_bf16 v[116:119], v[140:143], v[228:231], v[116:119]
	v_mfma_f32_16x16x32_bf16 v[100:103], v[140:143], v[240:243], v[100:103]
	v_mfma_f32_16x16x32_bf16 v[96:99], v[196:199], v[240:243], v[96:99]
	v_mfma_f32_16x16x32_bf16 v[80:83], v[196:199], v[244:247], v[80:83]
	v_mfma_f32_16x16x32_bf16 v[84:87], v[140:143], v[244:247], v[84:87]
	v_mfma_f32_16x16x32_bf16 v[124:127], v[200:203], v[216:219], v[124:127]
	v_mfma_f32_16x16x32_bf16 v[120:123], v[208:211], v[216:219], v[120:123]
	v_mfma_f32_16x16x32_bf16 v[104:107], v[208:211], v[220:223], v[104:107]
	v_mfma_f32_16x16x32_bf16 v[108:111], v[200:203], v[220:223], v[108:111]
	v_mfma_f32_16x16x32_bf16 v[92:95], v[200:203], v[232:235], v[92:95]
	v_mfma_f32_16x16x32_bf16 v[88:91], v[208:211], v[232:235], v[88:91]
	v_mfma_f32_16x16x32_bf16 v[72:75], v[208:211], v[236:239], v[72:75]
	v_mfma_f32_16x16x32_bf16 v[76:79], v[200:203], v[236:239], v[76:79]
	v_mfma_f32_16x16x32_bf16 v[124:127], v[204:207], v[224:227], v[124:127]
	v_mfma_f32_16x16x32_bf16 v[120:123], v[212:215], v[224:227], v[120:123]
	v_mfma_f32_16x16x32_bf16 v[104:107], v[212:215], v[228:231], v[104:107]
	v_mfma_f32_16x16x32_bf16 v[108:111], v[204:207], v[228:231], v[108:111]
	v_mfma_f32_16x16x32_bf16 v[92:95], v[204:207], v[240:243], v[92:95]
	v_mfma_f32_16x16x32_bf16 v[88:91], v[212:215], v[240:243], v[88:91]
	v_mfma_f32_16x16x32_bf16 v[72:75], v[212:215], v[244:247], v[72:75]
	v_mfma_f32_16x16x32_bf16 v[76:79], v[204:207], v[244:247], v[76:79]
	s_barrier
	s_add_i32 s26, s83, s3
	v_lshl_add_u64 v[10:11], v[184:185], 0, s[24:25]
	s_mov_b32 m0, s26
	ds_read_b128 v[216:219], v176 offset:49152
	ds_read_b128 v[220:223], v176 offset:51200
	ds_read_b128 v[224:227], v177 offset:49152
	ds_read_b128 v[228:231], v177 offset:51200
	ds_read_b128 v[232:235], v176 offset:53248
	ds_read_b128 v[236:239], v176 offset:55296
	ds_read_b128 v[240:243], v177 offset:53248
	ds_read_b128 v[244:247], v177 offset:55296
	global_load_lds_dwordx4 v[10:11], off
	v_lshl_add_u64 v[10:11], v[184:185], 0, s[50:51]
	s_add_i32 m0, s26, 0x2000
	s_add_i32 s26, s84, s3
	global_load_lds_dwordx4 v[10:11], off
	v_lshl_add_u64 v[10:11], v[184:185], 0, s[52:53]
	s_mov_b32 m0, s26
	s_nop 0
	global_load_lds_dwordx4 v[10:11], off
	v_lshl_add_u64 v[10:11], v[184:185], 0, s[54:55]
	s_add_i32 m0, s26, 0x2000
	s_nop 0
	global_load_lds_dwordx4 v[10:11], off
	s_waitcnt vmcnt(4)
	s_waitcnt lgkmcnt(0)
	s_barrier
	v_mfma_f32_16x16x32_bf16 v[68:71], v[136:139], v[216:219], v[68:71]
	v_mfma_f32_16x16x32_bf16 v[64:67], v[180:183], v[216:219], v[64:67]
	v_mfma_f32_16x16x32_bf16 v[48:51], v[180:183], v[220:223], v[48:51]
	v_mfma_f32_16x16x32_bf16 v[52:55], v[136:139], v[220:223], v[52:55]
	v_mfma_f32_16x16x32_bf16 v[36:39], v[136:139], v[232:235], v[36:39]
	v_mfma_f32_16x16x32_bf16 v[32:35], v[180:183], v[232:235], v[32:35]
	v_mfma_f32_16x16x32_bf16 v[16:19], v[180:183], v[236:239], v[16:19]
	v_mfma_f32_16x16x32_bf16 v[20:23], v[136:139], v[236:239], v[20:23]
	v_mfma_f32_16x16x32_bf16 v[68:71], v[140:143], v[224:227], v[68:71]
	v_mfma_f32_16x16x32_bf16 v[64:67], v[196:199], v[224:227], v[64:67]
	v_mfma_f32_16x16x32_bf16 v[48:51], v[196:199], v[228:231], v[48:51]
	v_mfma_f32_16x16x32_bf16 v[52:55], v[140:143], v[228:231], v[52:55]
	v_mfma_f32_16x16x32_bf16 v[36:39], v[140:143], v[240:243], v[36:39]
	v_mfma_f32_16x16x32_bf16 v[32:35], v[196:199], v[240:243], v[32:35]
	v_mfma_f32_16x16x32_bf16 v[16:19], v[196:199], v[244:247], v[16:19]
	v_mfma_f32_16x16x32_bf16 v[20:23], v[140:143], v[244:247], v[20:23]
	v_mfma_f32_16x16x32_bf16 v[60:63], v[200:203], v[216:219], v[60:63]
	v_mfma_f32_16x16x32_bf16 v[56:59], v[208:211], v[216:219], v[56:59]
	v_mfma_f32_16x16x32_bf16 v[40:43], v[208:211], v[220:223], v[40:43]
	v_mfma_f32_16x16x32_bf16 v[44:47], v[200:203], v[220:223], v[44:47]
	v_mfma_f32_16x16x32_bf16 v[28:31], v[200:203], v[232:235], v[28:31]
	v_mfma_f32_16x16x32_bf16 v[24:27], v[208:211], v[232:235], v[24:27]
	v_mfma_f32_16x16x32_bf16 v[6:9], v[208:211], v[236:239], v[6:9]
	v_mfma_f32_16x16x32_bf16 v[10:13], v[200:203], v[236:239], v[12:15]
	v_mfma_f32_16x16x32_bf16 v[60:63], v[204:207], v[224:227], v[60:63]
	v_mfma_f32_16x16x32_bf16 v[56:59], v[212:215], v[224:227], v[56:59]
	v_mfma_f32_16x16x32_bf16 v[40:43], v[212:215], v[228:231], v[40:43]
	v_mfma_f32_16x16x32_bf16 v[44:47], v[204:207], v[228:231], v[44:47]
	v_mfma_f32_16x16x32_bf16 v[28:31], v[204:207], v[240:243], v[28:31]
	v_mfma_f32_16x16x32_bf16 v[24:27], v[212:215], v[240:243], v[24:27]
	v_mfma_f32_16x16x32_bf16 v[8:11], v[212:215], v[244:247], v[6:9]
	v_mfma_f32_16x16x32_bf16 v[12:15], v[204:207], v[244:247], v[10:13]
	s_barrier
	s_add_i32 s95, s95, 2
	s_add_u32 s64, s64, 0x100
	s_addc_u32 s65, s65, 0
	s_cmp_gt_u32 s95, 21
	s_cbranch_scc1 .LBB0_782

.LBB0_973:
	v_add_u32_e32 v133, s72, v163
	v_add_u32_e32 v140, s72, v164
	ds_read_b128 v[136:139], v133
	ds_read_b128 v[148:151], v140
	v_add_u32_e32 v133, s73, v163
	s_add_u32 s70, s28, s26
	v_add_u32_e32 v140, s73, v164
	s_waitcnt lgkmcnt(0)
	ds_read_b128 v[152:155], v133
	ds_read_b128 v[174:177], v140
	v_add_u32_e32 v133, s77, v163
	s_addc_u32 s71, s29, s27
	v_add_u32_e32 v140, s77, v164
	ds_read_b128 v[178:181], v133
	ds_read_b128 v[182:185], v140
	v_add_u32_e32 v133, s79, v163
	s_add_u32 s70, s70, 0x100
	v_add_u32_e32 v140, s79, v164
	ds_read_b128 v[196:199], v133
	ds_read_b128 v[200:203], v140
	s_addc_u32 s71, s71, 0
	s_add_u32 s86, s65, s26
	s_addc_u32 s87, s85, s27
	s_cmpk_eq_i32 s26, 0x700
	s_cselect_b32 s87, s61, s87
	s_cselect_b32 s86, s88, s86
	s_cselect_b32 s71, s54, s71
	s_cselect_b32 s70, s63, s70
	v_lshl_add_u64 v[140:141], v[134:135], 0, s[26:27]
	v_lshl_add_u64 v[160:161], v[140:141], 0, s[36:37]
	s_add_i32 m0, s5, 0x8000
	s_mov_b64 s[90:91], 0x20080
	ds_read_b128 v[204:207], v166
	ds_read_b128 v[208:211], v166 offset:2048
	ds_read_b128 v[212:215], v167
	ds_read_b128 v[216:219], v167 offset:2048
	ds_read_b128 v[220:223], v166 offset:4096
	ds_read_b128 v[224:227], v166 offset:6144
	ds_read_b128 v[228:231], v167 offset:4096
	ds_read_b128 v[232:235], v167 offset:6144
	global_load_lds_dwordx4 v[160:161], off
	v_lshl_add_u64 v[160:161], v[140:141], 0, s[90:91]
	s_add_i32 m0, s5, 0xa000
	s_mov_b64 s[90:91], 0x60080
	global_load_lds_dwordx4 v[160:161], off
	v_lshl_add_u64 v[160:161], v[140:141], 0, s[44:45]
	s_add_i32 m0, s5, 0xc000
	v_lshl_add_u64 v[140:141], v[140:141], 0, s[90:91]
	global_load_lds_dwordx4 v[160:161], off
	s_add_i32 m0, s5, 0xe000
	s_nop 0
	global_load_lds_dwordx4 v[140:141], off
	s_waitcnt vmcnt(8)
	s_waitcnt lgkmcnt(0)
	s_barrier
	v_mfma_f32_16x16x32_bf16 v[8:11], v[136:139], v[204:207], v[8:11]
	v_mfma_f32_16x16x32_bf16 v[4:7], v[152:155], v[204:207], v[4:7]
	v_mfma_f32_16x16x32_bf16 v[16:19], v[152:155], v[208:211], v[16:19]
	v_mfma_f32_16x16x32_bf16 v[12:15], v[136:139], v[208:211], v[12:15]
	v_mfma_f32_16x16x32_bf16 v[44:47], v[136:139], v[220:223], v[44:47]
	v_mfma_f32_16x16x32_bf16 v[36:39], v[152:155], v[220:223], v[36:39]
	v_mfma_f32_16x16x32_bf16 v[24:27], v[152:155], v[224:227], v[24:27]
	v_mfma_f32_16x16x32_bf16 v[20:23], v[136:139], v[224:227], v[20:23]
	v_mfma_f32_16x16x32_bf16 v[8:11], v[148:151], v[212:215], v[8:11]
	v_mfma_f32_16x16x32_bf16 v[4:7], v[174:177], v[212:215], v[4:7]
	v_mfma_f32_16x16x32_bf16 v[16:19], v[174:177], v[216:219], v[16:19]
	v_mfma_f32_16x16x32_bf16 v[12:15], v[148:151], v[216:219], v[12:15]
	v_mfma_f32_16x16x32_bf16 v[44:47], v[148:151], v[228:231], v[44:47]
	v_mfma_f32_16x16x32_bf16 v[36:39], v[174:177], v[228:231], v[36:39]
	v_mfma_f32_16x16x32_bf16 v[24:27], v[174:177], v[232:235], v[24:27]
	v_mfma_f32_16x16x32_bf16 v[20:23], v[148:151], v[232:235], v[20:23]
	v_mfma_f32_16x16x32_bf16 v[32:35], v[178:181], v[204:207], v[32:35]
	v_mfma_f32_16x16x32_bf16 v[28:31], v[196:199], v[204:207], v[28:31]
	v_mfma_f32_16x16x32_bf16 v[52:55], v[196:199], v[208:211], v[52:55]
	v_mfma_f32_16x16x32_bf16 v[40:43], v[178:181], v[208:211], v[40:43]
	v_mfma_f32_16x16x32_bf16 v[48:51], v[178:181], v[220:223], v[48:51]
	v_mfma_f32_16x16x32_bf16 v[60:63], v[196:199], v[220:223], v[60:63]
	v_mfma_f32_16x16x32_bf16 v[64:67], v[196:199], v[224:227], v[64:67]
	v_mfma_f32_16x16x32_bf16 v[56:59], v[178:181], v[224:227], v[56:59]
	v_mfma_f32_16x16x32_bf16 v[32:35], v[182:185], v[212:215], v[32:35]
	v_mfma_f32_16x16x32_bf16 v[28:31], v[200:203], v[212:215], v[28:31]
	v_mfma_f32_16x16x32_bf16 v[52:55], v[200:203], v[216:219], v[52:55]
	v_mfma_f32_16x16x32_bf16 v[40:43], v[182:185], v[216:219], v[40:43]
	v_mfma_f32_16x16x32_bf16 v[48:51], v[182:185], v[228:231], v[48:51]
	v_mfma_f32_16x16x32_bf16 v[60:63], v[200:203], v[228:231], v[60:63]
	v_mfma_f32_16x16x32_bf16 v[64:67], v[200:203], v[232:235], v[64:67]
	v_mfma_f32_16x16x32_bf16 v[56:59], v[182:185], v[232:235], v[56:59]
	s_barrier
	v_lshl_add_u64 v[140:141], s[86:87], 0, v[158:159]
	s_add_i32 s86, s72, s34
	s_mov_b32 m0, s86
	ds_read_b128 v[204:207], v166 offset:16384
	ds_read_b128 v[208:211], v166 offset:18432
	ds_read_b128 v[212:215], v167 offset:16384
	ds_read_b128 v[216:219], v167 offset:18432
	ds_read_b128 v[220:223], v166 offset:20480
	ds_read_b128 v[224:227], v166 offset:22528
	ds_read_b128 v[228:231], v167 offset:20480
	ds_read_b128 v[232:235], v167 offset:22528
	global_load_lds_dwordx4 v[140:141], off
	v_lshl_add_u64 v[160:161], v[140:141], 0, s[18:19]
	s_add_i32 m0, s86, 0x2000
	s_mov_b64 s[86:87], 0x10000
	global_load_lds_dwordx4 v[160:161], off
	v_lshl_add_u64 v[160:161], v[140:141], 0, s[86:87]
	s_add_i32 s86, s77, s34
	s_mov_b32 m0, s86
	s_nop 0
	global_load_lds_dwordx4 v[160:161], off
	v_lshl_add_u64 v[160:161], v[140:141], 0, s[20:21]
	s_add_i32 m0, s86, 0x2000
	s_nop 0
	global_load_lds_dwordx4 v[160:161], off
	s_waitcnt vmcnt(4)
	s_waitcnt lgkmcnt(0)
	s_barrier
	v_mfma_f32_16x16x32_bf16 v[68:71], v[136:139], v[204:207], v[68:71]
	v_mfma_f32_16x16x32_bf16 v[72:75], v[152:155], v[204:207], v[72:75]
	v_mfma_f32_16x16x32_bf16 v[84:87], v[152:155], v[208:211], v[84:87]
	v_mfma_f32_16x16x32_bf16 v[92:95], v[136:139], v[208:211], v[92:95]
	v_mfma_f32_16x16x32_bf16 v[76:79], v[136:139], v[220:223], v[76:79]
	v_mfma_f32_16x16x32_bf16 v[80:83], v[152:155], v[220:223], v[80:83]
	v_mfma_f32_16x16x32_bf16 v[108:111], v[152:155], v[224:227], v[108:111]
	v_mfma_f32_16x16x32_bf16 v[116:119], v[136:139], v[224:227], v[116:119]
	v_mfma_f32_16x16x32_bf16 v[68:71], v[148:151], v[212:215], v[68:71]
	v_mfma_f32_16x16x32_bf16 v[72:75], v[174:177], v[212:215], v[72:75]
	v_mfma_f32_16x16x32_bf16 v[84:87], v[174:177], v[216:219], v[84:87]
	v_mfma_f32_16x16x32_bf16 v[92:95], v[148:151], v[216:219], v[92:95]
	v_mfma_f32_16x16x32_bf16 v[76:79], v[148:151], v[228:231], v[76:79]
	v_mfma_f32_16x16x32_bf16 v[80:83], v[174:177], v[228:231], v[80:83]
	v_mfma_f32_16x16x32_bf16 v[108:111], v[174:177], v[232:235], v[108:111]
	v_mfma_f32_16x16x32_bf16 v[116:119], v[148:151], v[232:235], v[116:119]
	v_mfma_f32_16x16x32_bf16 v[88:91], v[178:181], v[204:207], v[88:91]
	v_mfma_f32_16x16x32_bf16 v[100:103], v[196:199], v[204:207], v[100:103]
	v_mfma_f32_16x16x32_bf16 v[104:107], v[196:199], v[208:211], v[104:107]
	v_mfma_f32_16x16x32_bf16 v[96:99], v[178:181], v[208:211], v[96:99]
	v_mfma_f32_16x16x32_bf16 v[112:115], v[178:181], v[220:223], v[112:115]
	v_mfma_f32_16x16x32_bf16 v[124:127], v[196:199], v[220:223], v[124:127]
	v_mfma_f32_16x16x32_bf16 v[128:131], v[196:199], v[224:227], v[128:131]
	v_mfma_f32_16x16x32_bf16 v[120:123], v[178:181], v[224:227], v[120:123]
	v_mfma_f32_16x16x32_bf16 v[88:91], v[182:185], v[212:215], v[88:91]
	v_mfma_f32_16x16x32_bf16 v[100:103], v[200:203], v[212:215], v[100:103]
	v_mfma_f32_16x16x32_bf16 v[104:107], v[200:203], v[216:219], v[104:107]
	v_mfma_f32_16x16x32_bf16 v[96:99], v[182:185], v[216:219], v[96:99]
	v_mfma_f32_16x16x32_bf16 v[112:115], v[182:185], v[228:231], v[112:115]
	v_mfma_f32_16x16x32_bf16 v[124:127], v[200:203], v[228:231], v[124:127]
	v_mfma_f32_16x16x32_bf16 v[128:131], v[200:203], v[232:235], v[128:131]
	v_mfma_f32_16x16x32_bf16 v[120:123], v[182:185], v[232:235], v[120:123]
	s_barrier
	v_add_u32_e32 v133, s82, v163
	v_add_u32_e32 v148, s82, v164
	ds_read_b128 v[136:139], v133
	ds_read_b128 v[148:151], v148
	v_add_u32_e32 v133, s80, v163
	v_add_u32_e32 v160, s80, v164
	ds_read_b128 v[152:155], v133
	ds_read_b128 v[174:177], v160
	v_add_u32_e32 v133, s83, v163
	v_add_u32_e32 v160, s83, v164
	ds_read_b128 v[178:181], v133
	ds_read_b128 v[182:185], v160
	v_add_u32_e32 v133, s81, v163
	v_add_u32_e32 v160, s81, v164
	ds_read_b128 v[196:199], v133
	ds_read_b128 v[200:203], v160
	s_mov_b32 m0, s5
	v_lshl_add_u64 v[160:161], s[70:71], 0, v[0:1]
	s_mov_b64 s[70:71], 0x20000
	ds_read_b128 v[204:207], v166 offset:32768
	ds_read_b128 v[208:211], v166 offset:34816
	ds_read_b128 v[212:215], v167 offset:32768
	ds_read_b128 v[216:219], v167 offset:34816
	ds_read_b128 v[220:223], v166 offset:36864
	ds_read_b128 v[224:227], v166 offset:38912
	ds_read_b128 v[228:231], v167 offset:36864
	ds_read_b128 v[232:235], v167 offset:38912
	global_load_lds_dwordx4 v[160:161], off
	v_lshl_add_u64 v[170:171], v[160:161], 0, s[70:71]
	s_mov_b32 m0, s17
	s_nop 0
	global_load_lds_dwordx4 v[170:171], off
	v_lshl_add_u64 v[170:171], v[160:161], 0, s[18:19]
	s_mov_b32 m0, s35
	v_lshl_add_u64 v[160:161], v[160:161], 0, s[22:23]
	global_load_lds_dwordx4 v[170:171], off
	s_mov_b32 m0, s38
	s_nop 0
	global_load_lds_dwordx4 v[160:161], off
	s_waitcnt vmcnt(8)
	s_waitcnt lgkmcnt(0)
	s_barrier
	v_mfma_f32_16x16x32_bf16 v[8:11], v[136:139], v[204:207], v[8:11]
	v_mfma_f32_16x16x32_bf16 v[4:7], v[152:155], v[204:207], v[4:7]
	v_mfma_f32_16x16x32_bf16 v[16:19], v[152:155], v[208:211], v[16:19]
	v_mfma_f32_16x16x32_bf16 v[12:15], v[136:139], v[208:211], v[12:15]
	v_mfma_f32_16x16x32_bf16 v[44:47], v[136:139], v[220:223], v[44:47]
	v_mfma_f32_16x16x32_bf16 v[36:39], v[152:155], v[220:223], v[36:39]
	v_mfma_f32_16x16x32_bf16 v[24:27], v[152:155], v[224:227], v[24:27]
	v_mfma_f32_16x16x32_bf16 v[20:23], v[136:139], v[224:227], v[20:23]
	v_mfma_f32_16x16x32_bf16 v[8:11], v[148:151], v[212:215], v[8:11]
	v_mfma_f32_16x16x32_bf16 v[4:7], v[174:177], v[212:215], v[4:7]
	v_mfma_f32_16x16x32_bf16 v[16:19], v[174:177], v[216:219], v[16:19]
	v_mfma_f32_16x16x32_bf16 v[12:15], v[148:151], v[216:219], v[12:15]
	v_mfma_f32_16x16x32_bf16 v[44:47], v[148:151], v[228:231], v[44:47]
	v_mfma_f32_16x16x32_bf16 v[36:39], v[174:177], v[228:231], v[36:39]
	v_mfma_f32_16x16x32_bf16 v[24:27], v[174:177], v[232:235], v[24:27]
	v_mfma_f32_16x16x32_bf16 v[20:23], v[148:151], v[232:235], v[20:23]
	v_mfma_f32_16x16x32_bf16 v[32:35], v[178:181], v[204:207], v[32:35]
	v_mfma_f32_16x16x32_bf16 v[28:31], v[196:199], v[204:207], v[28:31]
	v_mfma_f32_16x16x32_bf16 v[52:55], v[196:199], v[208:211], v[52:55]
	v_mfma_f32_16x16x32_bf16 v[40:43], v[178:181], v[208:211], v[40:43]
	v_mfma_f32_16x16x32_bf16 v[48:51], v[178:181], v[220:223], v[48:51]
	v_mfma_f32_16x16x32_bf16 v[60:63], v[196:199], v[220:223], v[60:63]
	v_mfma_f32_16x16x32_bf16 v[64:67], v[196:199], v[224:227], v[64:67]
	v_mfma_f32_16x16x32_bf16 v[56:59], v[178:181], v[224:227], v[56:59]
	v_mfma_f32_16x16x32_bf16 v[32:35], v[182:185], v[212:215], v[32:35]
	v_mfma_f32_16x16x32_bf16 v[28:31], v[200:203], v[212:215], v[28:31]
	v_mfma_f32_16x16x32_bf16 v[52:55], v[200:203], v[216:219], v[52:55]
	v_mfma_f32_16x16x32_bf16 v[40:43], v[182:185], v[216:219], v[40:43]
	v_mfma_f32_16x16x32_bf16 v[48:51], v[182:185], v[228:231], v[48:51]
	v_mfma_f32_16x16x32_bf16 v[60:63], v[200:203], v[228:231], v[60:63]
	v_mfma_f32_16x16x32_bf16 v[64:67], v[200:203], v[232:235], v[64:67]
	v_mfma_f32_16x16x32_bf16 v[56:59], v[182:185], v[232:235], v[56:59]
	s_barrier
	s_add_i32 s70, s82, s34
	v_lshl_add_u64 v[160:161], v[140:141], 0, s[36:37]
	s_mov_b32 m0, s70
	ds_read_b128 v[204:207], v166 offset:49152
	ds_read_b128 v[208:211], v166 offset:51200
	ds_read_b128 v[212:215], v167 offset:49152
	ds_read_b128 v[216:219], v167 offset:51200
	ds_read_b128 v[220:223], v166 offset:53248
	ds_read_b128 v[224:227], v166 offset:55296
	ds_read_b128 v[228:231], v167 offset:53248
	ds_read_b128 v[232:235], v167 offset:55296
	global_load_lds_dwordx4 v[160:161], off
	v_lshl_add_u64 v[160:161], v[140:141], 0, s[44:45]
	s_add_i32 m0, s70, 0x2000
	s_add_i32 s70, s83, s34
	global_load_lds_dwordx4 v[160:161], off
	v_lshl_add_u64 v[160:161], v[140:141], 0, s[46:47]
	s_mov_b32 m0, s70
	v_lshl_add_u64 v[140:141], v[140:141], 0, s[50:51]
	global_load_lds_dwordx4 v[160:161], off
	s_add_i32 m0, s70, 0x2000
	s_nop 0
	global_load_lds_dwordx4 v[140:141], off
	s_waitcnt vmcnt(4)
	s_waitcnt lgkmcnt(0)
	s_barrier
	v_mfma_f32_16x16x32_bf16 v[68:71], v[136:139], v[204:207], v[68:71]
	v_mfma_f32_16x16x32_bf16 v[72:75], v[152:155], v[204:207], v[72:75]
	v_mfma_f32_16x16x32_bf16 v[84:87], v[152:155], v[208:211], v[84:87]
	v_mfma_f32_16x16x32_bf16 v[92:95], v[136:139], v[208:211], v[92:95]
	v_mfma_f32_16x16x32_bf16 v[76:79], v[136:139], v[220:223], v[76:79]
	v_mfma_f32_16x16x32_bf16 v[80:83], v[152:155], v[220:223], v[80:83]
	v_mfma_f32_16x16x32_bf16 v[108:111], v[152:155], v[224:227], v[108:111]
	v_mfma_f32_16x16x32_bf16 v[116:119], v[136:139], v[224:227], v[116:119]
	v_mfma_f32_16x16x32_bf16 v[68:71], v[148:151], v[212:215], v[68:71]
	v_mfma_f32_16x16x32_bf16 v[72:75], v[174:177], v[212:215], v[72:75]
	v_mfma_f32_16x16x32_bf16 v[84:87], v[174:177], v[216:219], v[84:87]
	v_mfma_f32_16x16x32_bf16 v[92:95], v[148:151], v[216:219], v[92:95]
	v_mfma_f32_16x16x32_bf16 v[76:79], v[148:151], v[228:231], v[76:79]
	v_mfma_f32_16x16x32_bf16 v[80:83], v[174:177], v[228:231], v[80:83]
	v_mfma_f32_16x16x32_bf16 v[108:111], v[174:177], v[232:235], v[108:111]
	v_mfma_f32_16x16x32_bf16 v[116:119], v[148:151], v[232:235], v[116:119]
	v_mfma_f32_16x16x32_bf16 v[88:91], v[178:181], v[204:207], v[88:91]
	v_mfma_f32_16x16x32_bf16 v[100:103], v[196:199], v[204:207], v[100:103]
	v_mfma_f32_16x16x32_bf16 v[104:107], v[196:199], v[208:211], v[104:107]
	v_mfma_f32_16x16x32_bf16 v[96:99], v[178:181], v[208:211], v[96:99]
	v_mfma_f32_16x16x32_bf16 v[112:115], v[178:181], v[220:223], v[112:115]
	v_mfma_f32_16x16x32_bf16 v[124:127], v[196:199], v[220:223], v[124:127]
	v_mfma_f32_16x16x32_bf16 v[128:131], v[196:199], v[224:227], v[128:131]
	v_mfma_f32_16x16x32_bf16 v[120:123], v[178:181], v[224:227], v[120:123]
	v_mfma_f32_16x16x32_bf16 v[88:91], v[182:185], v[212:215], v[88:91]
	v_mfma_f32_16x16x32_bf16 v[100:103], v[200:203], v[212:215], v[100:103]
	v_mfma_f32_16x16x32_bf16 v[104:107], v[200:203], v[216:219], v[104:107]
	v_mfma_f32_16x16x32_bf16 v[96:99], v[182:185], v[216:219], v[96:99]
	v_mfma_f32_16x16x32_bf16 v[112:115], v[182:185], v[228:231], v[112:115]
	v_mfma_f32_16x16x32_bf16 v[124:127], v[200:203], v[228:231], v[124:127]
	v_mfma_f32_16x16x32_bf16 v[128:131], v[200:203], v[232:235], v[128:131]
	v_mfma_f32_16x16x32_bf16 v[120:123], v[182:185], v[232:235], v[120:123]
	s_barrier
	s_add_i32 s89, s89, 2
	s_add_u32 s26, s26, 0x100
	s_addc_u32 s27, s27, 0
	s_cmp_gt_u32 s89, 13
	s_cbranch_scc0 .LBB0_973
	s_and_b64 vcc, exec, s[52:53]
	s_cbranch_vccz .LBB0_976
	s_barrier

.LBB0_1134:
	s_ashr_i32 s57, s56, 31
	s_lshl_b64 s[60:61], s[56:57], 19
	s_add_u32 s60, s42, s60
	s_addc_u32 s61, s43, s61
	s_and_b64 s[62:63], s[10:11], exec
	s_cselect_b32 s57, s61, s27
	s_cselect_b32 s79, s60, s26
	s_ashr_i32 s59, s58, 31
	s_lshl_b64 s[62:63], s[58:59], 19
	v_readlane_b32 s70, v254, 7
	v_readlane_b32 s71, v254, 8
	s_add_u32 s62, s70, s62
	s_addc_u32 s63, s71, s63
	s_and_b64 s[70:71], s[10:11], exec
	s_cselect_b32 s59, s63, s69
	s_cselect_b32 s80, s62, s68
	s_add_u32 s81, s68, 0x100
	v_lshl_add_u64 v[138:139], s[26:27], 0, v[132:133]
	s_addc_u32 s82, s69, 0
	s_mov_b32 s83, -2
	s_mov_b64 s[68:69], 0
	ds_read_b128 v[168:171], v145
	ds_read_b128 v[174:177], v146
	ds_read_b128 v[178:181], v147
	ds_read_b128 v[182:185], v148
	ds_read_b128 v[194:197], v149
	ds_read_b128 v[198:201], v150
	ds_read_b128 v[202:205], v151
	ds_read_b128 v[206:209], v152
	s_add_u32 s70, s26, s68
	s_addc_u32 s71, s27, s69
	s_add_u32 s70, s70, 0x100
	s_addc_u32 s71, s71, 0
	s_add_u32 s84, s81, s68
	s_addc_u32 s85, s82, s69
	s_cmpk_eq_i32 s68, 0x700
	s_cselect_b32 s85, s59, s85
	s_cselect_b32 s84, s80, s84
	s_cselect_b32 s71, s57, s71
	s_cselect_b32 s70, s79, s70
	v_lshl_add_u64 v[140:141], v[138:139], 0, s[68:69]
	v_lshl_add_u64 v[242:243], v[140:141], 0, s[22:23]
	s_add_i32 m0, s34, 0x8000
	s_mov_b64 s[86:87], 0x20080
	ds_read_b128 v[210:213], v153
	ds_read_b128 v[214:217], v153 offset:2048
	ds_read_b128 v[218:221], v154
	ds_read_b128 v[222:225], v154 offset:2048
	ds_read_b128 v[226:229], v153 offset:4096
	ds_read_b128 v[230:233], v153 offset:6144
	ds_read_b128 v[234:237], v154 offset:4096
	ds_read_b128 v[238:241], v154 offset:6144
	global_load_lds_dwordx4 v[242:243], off
	v_lshl_add_u64 v[242:243], v[140:141], 0, s[86:87]
	s_add_i32 m0, s34, 0xa000
	s_mov_b64 s[86:87], 0x60080
	global_load_lds_dwordx4 v[242:243], off
	v_lshl_add_u64 v[242:243], v[140:141], 0, s[24:25]
	s_add_i32 m0, s34, 0xc000
	v_lshl_add_u64 v[140:141], v[140:141], 0, s[86:87]
	global_load_lds_dwordx4 v[242:243], off
	s_add_i32 m0, s34, 0xe000
	s_nop 0
	global_load_lds_dwordx4 v[140:141], off
	s_waitcnt lgkmcnt(0)
	s_barrier
	v_mfma_f32_16x16x32_bf16 v[128:131], v[168:171], v[210:213], 0
	v_mfma_f32_16x16x32_bf16 v[124:127], v[178:181], v[210:213], 0
	v_mfma_f32_16x16x32_bf16 v[108:111], v[178:181], v[214:217], 0
	v_mfma_f32_16x16x32_bf16 v[112:115], v[168:171], v[214:217], 0
	v_mfma_f32_16x16x32_bf16 v[96:99], v[168:171], v[226:229], 0
	v_mfma_f32_16x16x32_bf16 v[92:95], v[178:181], v[226:229], 0
	v_mfma_f32_16x16x32_bf16 v[76:79], v[178:181], v[230:233], 0
	v_mfma_f32_16x16x32_bf16 v[80:83], v[168:171], v[230:233], 0
	v_mfma_f32_16x16x32_bf16 v[128:131], v[174:177], v[218:221], v[128:131]
	v_mfma_f32_16x16x32_bf16 v[124:127], v[182:185], v[218:221], v[124:127]
	v_mfma_f32_16x16x32_bf16 v[108:111], v[182:185], v[222:225], v[108:111]
	v_mfma_f32_16x16x32_bf16 v[112:115], v[174:177], v[222:225], v[112:115]
	v_mfma_f32_16x16x32_bf16 v[96:99], v[174:177], v[234:237], v[96:99]
	v_mfma_f32_16x16x32_bf16 v[92:95], v[182:185], v[234:237], v[92:95]
	v_mfma_f32_16x16x32_bf16 v[76:79], v[182:185], v[238:241], v[76:79]
	v_mfma_f32_16x16x32_bf16 v[80:83], v[174:177], v[238:241], v[80:83]
	v_mfma_f32_16x16x32_bf16 v[120:123], v[194:197], v[210:213], 0
	v_mfma_f32_16x16x32_bf16 v[116:119], v[202:205], v[210:213], 0
	v_mfma_f32_16x16x32_bf16 v[100:103], v[202:205], v[214:217], 0
	v_mfma_f32_16x16x32_bf16 v[104:107], v[194:197], v[214:217], 0
	v_mfma_f32_16x16x32_bf16 v[88:91], v[194:197], v[226:229], 0
	v_mfma_f32_16x16x32_bf16 v[84:87], v[202:205], v[226:229], 0
	v_mfma_f32_16x16x32_bf16 v[68:71], v[202:205], v[230:233], 0
	v_mfma_f32_16x16x32_bf16 v[72:75], v[194:197], v[230:233], 0
	v_mfma_f32_16x16x32_bf16 v[120:123], v[198:201], v[218:221], v[120:123]
	v_mfma_f32_16x16x32_bf16 v[116:119], v[206:209], v[218:221], v[116:119]
	v_mfma_f32_16x16x32_bf16 v[100:103], v[206:209], v[222:225], v[100:103]
	v_mfma_f32_16x16x32_bf16 v[104:107], v[198:201], v[222:225], v[104:107]
	v_mfma_f32_16x16x32_bf16 v[88:91], v[198:201], v[234:237], v[88:91]
	v_mfma_f32_16x16x32_bf16 v[84:87], v[206:209], v[234:237], v[84:87]
	v_mfma_f32_16x16x32_bf16 v[68:71], v[206:209], v[238:241], v[68:71]
	v_mfma_f32_16x16x32_bf16 v[72:75], v[198:201], v[238:241], v[72:75]
	s_barrier
	v_lshl_add_u64 v[140:141], s[84:85], 0, v[158:159]
	s_add_i32 s84, s67, s3
	s_mov_b32 m0, s84
	ds_read_b128 v[210:213], v153 offset:16384
	ds_read_b128 v[214:217], v153 offset:18432
	ds_read_b128 v[218:221], v154 offset:16384
	ds_read_b128 v[222:225], v154 offset:18432
	ds_read_b128 v[226:229], v153 offset:20480
	ds_read_b128 v[230:233], v153 offset:22528
	ds_read_b128 v[234:237], v154 offset:20480
	ds_read_b128 v[238:241], v154 offset:22528
	global_load_lds_dwordx4 v[140:141], off
	v_lshl_add_u64 v[242:243], v[140:141], 0, s[0:1]
	s_add_i32 m0, s84, 0x2000
	s_add_i32 s84, s72, s3
	global_load_lds_dwordx4 v[242:243], off
	v_lshl_add_u64 v[242:243], v[140:141], 0, s[12:13]
	s_mov_b32 m0, s84
	s_nop 0
	global_load_lds_dwordx4 v[242:243], off
	v_lshl_add_u64 v[242:243], v[140:141], 0, s[14:15]
	s_add_i32 m0, s84, 0x2000
	s_nop 0
	global_load_lds_dwordx4 v[242:243], off
	s_waitcnt vmcnt(4)
	s_waitcnt lgkmcnt(0)
	s_barrier
	v_mfma_f32_16x16x32_bf16 v[64:67], v[168:171], v[210:213], 0
	v_mfma_f32_16x16x32_bf16 v[60:63], v[178:181], v[210:213], 0
	v_mfma_f32_16x16x32_bf16 v[44:47], v[178:181], v[214:217], 0
	v_mfma_f32_16x16x32_bf16 v[48:51], v[168:171], v[214:217], 0
	v_mfma_f32_16x16x32_bf16 v[32:35], v[168:171], v[226:229], 0
	v_mfma_f32_16x16x32_bf16 v[28:31], v[178:181], v[226:229], 0
	v_mfma_f32_16x16x32_bf16 v[12:15], v[178:181], v[230:233], 0
	v_mfma_f32_16x16x32_bf16 v[16:19], v[168:171], v[230:233], 0
	v_mfma_f32_16x16x32_bf16 v[64:67], v[174:177], v[218:221], v[64:67]
	v_mfma_f32_16x16x32_bf16 v[60:63], v[182:185], v[218:221], v[60:63]
	v_mfma_f32_16x16x32_bf16 v[44:47], v[182:185], v[222:225], v[44:47]
	v_mfma_f32_16x16x32_bf16 v[48:51], v[174:177], v[222:225], v[48:51]
	v_mfma_f32_16x16x32_bf16 v[32:35], v[174:177], v[234:237], v[32:35]
	v_mfma_f32_16x16x32_bf16 v[28:31], v[182:185], v[234:237], v[28:31]
	v_mfma_f32_16x16x32_bf16 v[12:15], v[182:185], v[238:241], v[12:15]
	v_mfma_f32_16x16x32_bf16 v[16:19], v[174:177], v[238:241], v[16:19]
	v_mfma_f32_16x16x32_bf16 v[56:59], v[194:197], v[210:213], 0
	v_mfma_f32_16x16x32_bf16 v[52:55], v[202:205], v[210:213], 0
	v_mfma_f32_16x16x32_bf16 v[36:39], v[202:205], v[214:217], 0
	v_mfma_f32_16x16x32_bf16 v[40:43], v[194:197], v[214:217], 0
	v_mfma_f32_16x16x32_bf16 v[24:27], v[194:197], v[226:229], 0
	v_mfma_f32_16x16x32_bf16 v[20:23], v[202:205], v[226:229], 0
	v_mfma_f32_16x16x32_bf16 v[4:7], v[202:205], v[230:233], 0
	v_mfma_f32_16x16x32_bf16 v[8:11], v[194:197], v[230:233], 0
	v_mfma_f32_16x16x32_bf16 v[56:59], v[198:201], v[218:221], v[56:59]
	v_mfma_f32_16x16x32_bf16 v[52:55], v[206:209], v[218:221], v[52:55]
	v_mfma_f32_16x16x32_bf16 v[36:39], v[206:209], v[222:225], v[36:39]
	v_mfma_f32_16x16x32_bf16 v[40:43], v[198:201], v[222:225], v[40:43]
	v_mfma_f32_16x16x32_bf16 v[24:27], v[198:201], v[234:237], v[24:27]
	v_mfma_f32_16x16x32_bf16 v[20:23], v[206:209], v[234:237], v[20:23]
	v_mfma_f32_16x16x32_bf16 v[4:7], v[206:209], v[238:241], v[4:7]
	v_mfma_f32_16x16x32_bf16 v[8:11], v[198:201], v[238:241], v[8:11]
	s_barrier
	ds_read_b128 v[168:171], v163
	ds_read_b128 v[174:177], v164
	ds_read_b128 v[178:181], v155
	ds_read_b128 v[182:185], v160
	ds_read_b128 v[194:197], v165
	ds_read_b128 v[198:201], v166
	ds_read_b128 v[202:205], v161
	ds_read_b128 v[206:209], v162
	s_mov_b32 m0, s34
	v_lshl_add_u64 v[242:243], s[70:71], 0, v[0:1]
	ds_read_b128 v[210:213], v153 offset:32768
	ds_read_b128 v[214:217], v153 offset:34816
	ds_read_b128 v[218:221], v154 offset:32768
	ds_read_b128 v[222:225], v154 offset:34816
	ds_read_b128 v[226:229], v153 offset:36864
	ds_read_b128 v[230:233], v153 offset:38912
	ds_read_b128 v[234:237], v154 offset:36864
	ds_read_b128 v[238:241], v154 offset:38912
	global_load_lds_dwordx4 v[242:243], off
	v_lshl_add_u64 v[244:245], v[242:243], 0, s[16:17]
	s_mov_b32 m0, s35
	s_nop 0
	global_load_lds_dwordx4 v[244:245], off
	v_lshl_add_u64 v[244:245], v[242:243], 0, s[0:1]
	s_mov_b32 m0, s38
	v_lshl_add_u64 v[242:243], v[242:243], 0, s[18:19]
	global_load_lds_dwordx4 v[244:245], off
	s_mov_b32 m0, s39
	s_nop 0
	global_load_lds_dwordx4 v[242:243], off
	s_waitcnt vmcnt(8)
	s_waitcnt lgkmcnt(0)
	s_barrier
	v_mfma_f32_16x16x32_bf16 v[128:131], v[168:171], v[210:213], v[128:131]
	v_mfma_f32_16x16x32_bf16 v[124:127], v[178:181], v[210:213], v[124:127]
	v_mfma_f32_16x16x32_bf16 v[108:111], v[178:181], v[214:217], v[108:111]
	v_mfma_f32_16x16x32_bf16 v[112:115], v[168:171], v[214:217], v[112:115]
	v_mfma_f32_16x16x32_bf16 v[96:99], v[168:171], v[226:229], v[96:99]
	v_mfma_f32_16x16x32_bf16 v[92:95], v[178:181], v[226:229], v[92:95]
	v_mfma_f32_16x16x32_bf16 v[76:79], v[178:181], v[230:233], v[76:79]
	v_mfma_f32_16x16x32_bf16 v[80:83], v[168:171], v[230:233], v[80:83]
	v_mfma_f32_16x16x32_bf16 v[128:131], v[174:177], v[218:221], v[128:131]
	v_mfma_f32_16x16x32_bf16 v[124:127], v[182:185], v[218:221], v[124:127]
	v_mfma_f32_16x16x32_bf16 v[108:111], v[182:185], v[222:225], v[108:111]
	v_mfma_f32_16x16x32_bf16 v[112:115], v[174:177], v[222:225], v[112:115]
	v_mfma_f32_16x16x32_bf16 v[96:99], v[174:177], v[234:237], v[96:99]
	v_mfma_f32_16x16x32_bf16 v[92:95], v[182:185], v[234:237], v[92:95]
	v_mfma_f32_16x16x32_bf16 v[76:79], v[182:185], v[238:241], v[76:79]
	v_mfma_f32_16x16x32_bf16 v[80:83], v[174:177], v[238:241], v[80:83]
	v_mfma_f32_16x16x32_bf16 v[120:123], v[194:197], v[210:213], v[120:123]
	v_mfma_f32_16x16x32_bf16 v[116:119], v[202:205], v[210:213], v[116:119]
	v_mfma_f32_16x16x32_bf16 v[100:103], v[202:205], v[214:217], v[100:103]
	v_mfma_f32_16x16x32_bf16 v[104:107], v[194:197], v[214:217], v[104:107]
	v_mfma_f32_16x16x32_bf16 v[88:91], v[194:197], v[226:229], v[88:91]
	v_mfma_f32_16x16x32_bf16 v[84:87], v[202:205], v[226:229], v[84:87]
	v_mfma_f32_16x16x32_bf16 v[68:71], v[202:205], v[230:233], v[68:71]
	v_mfma_f32_16x16x32_bf16 v[72:75], v[194:197], v[230:233], v[72:75]
	v_mfma_f32_16x16x32_bf16 v[120:123], v[198:201], v[218:221], v[120:123]
	v_mfma_f32_16x16x32_bf16 v[116:119], v[206:209], v[218:221], v[116:119]
	v_mfma_f32_16x16x32_bf16 v[100:103], v[206:209], v[222:225], v[100:103]
	v_mfma_f32_16x16x32_bf16 v[104:107], v[198:201], v[222:225], v[104:107]
	v_mfma_f32_16x16x32_bf16 v[88:91], v[198:201], v[234:237], v[88:91]
	v_mfma_f32_16x16x32_bf16 v[84:87], v[206:209], v[234:237], v[84:87]
	v_mfma_f32_16x16x32_bf16 v[68:71], v[206:209], v[238:241], v[68:71]
	v_mfma_f32_16x16x32_bf16 v[72:75], v[198:201], v[238:241], v[72:75]
	s_barrier
	s_add_i32 s70, s73, s3
	v_lshl_add_u64 v[242:243], v[140:141], 0, s[22:23]
	s_mov_b32 m0, s70
	ds_read_b128 v[210:213], v153 offset:49152
	ds_read_b128 v[214:217], v153 offset:51200
	ds_read_b128 v[218:221], v154 offset:49152
	ds_read_b128 v[222:225], v154 offset:51200
	ds_read_b128 v[226:229], v153 offset:53248
	ds_read_b128 v[230:233], v153 offset:55296
	ds_read_b128 v[234:237], v154 offset:53248
	ds_read_b128 v[238:241], v154 offset:55296
	global_load_lds_dwordx4 v[242:243], off
	v_lshl_add_u64 v[242:243], v[140:141], 0, s[24:25]
	s_add_i32 m0, s70, 0x2000
	s_add_i32 s70, s77, s3
	global_load_lds_dwordx4 v[242:243], off
	v_lshl_add_u64 v[242:243], v[140:141], 0, s[28:29]
	s_mov_b32 m0, s70
	v_lshl_add_u64 v[140:141], v[140:141], 0, s[36:37]
	global_load_lds_dwordx4 v[242:243], off
	s_add_i32 m0, s70, 0x2000
	s_nop 0
	global_load_lds_dwordx4 v[140:141], off
	s_waitcnt vmcnt(4)
	s_waitcnt lgkmcnt(0)
	s_barrier
	v_mfma_f32_16x16x32_bf16 v[64:67], v[168:171], v[210:213], v[64:67]
	v_mfma_f32_16x16x32_bf16 v[60:63], v[178:181], v[210:213], v[60:63]
	v_mfma_f32_16x16x32_bf16 v[44:47], v[178:181], v[214:217], v[44:47]
	v_mfma_f32_16x16x32_bf16 v[48:51], v[168:171], v[214:217], v[48:51]
	v_mfma_f32_16x16x32_bf16 v[32:35], v[168:171], v[226:229], v[32:35]
	v_mfma_f32_16x16x32_bf16 v[28:31], v[178:181], v[226:229], v[28:31]
	v_mfma_f32_16x16x32_bf16 v[12:15], v[178:181], v[230:233], v[12:15]
	v_mfma_f32_16x16x32_bf16 v[16:19], v[168:171], v[230:233], v[16:19]
	v_mfma_f32_16x16x32_bf16 v[64:67], v[174:177], v[218:221], v[64:67]
	v_mfma_f32_16x16x32_bf16 v[60:63], v[182:185], v[218:221], v[60:63]
	v_mfma_f32_16x16x32_bf16 v[44:47], v[182:185], v[222:225], v[44:47]
	v_mfma_f32_16x16x32_bf16 v[48:51], v[174:177], v[222:225], v[48:51]
	v_mfma_f32_16x16x32_bf16 v[32:35], v[174:177], v[234:237], v[32:35]
	v_mfma_f32_16x16x32_bf16 v[28:31], v[182:185], v[234:237], v[28:31]
	v_mfma_f32_16x16x32_bf16 v[12:15], v[182:185], v[238:241], v[12:15]
	v_mfma_f32_16x16x32_bf16 v[16:19], v[174:177], v[238:241], v[16:19]
	v_mfma_f32_16x16x32_bf16 v[56:59], v[194:197], v[210:213], v[56:59]
	v_mfma_f32_16x16x32_bf16 v[52:55], v[202:205], v[210:213], v[52:55]
	v_mfma_f32_16x16x32_bf16 v[36:39], v[202:205], v[214:217], v[36:39]
	v_mfma_f32_16x16x32_bf16 v[40:43], v[194:197], v[214:217], v[40:43]
	v_mfma_f32_16x16x32_bf16 v[24:27], v[194:197], v[226:229], v[24:27]
	v_mfma_f32_16x16x32_bf16 v[20:23], v[202:205], v[226:229], v[20:23]
	v_mfma_f32_16x16x32_bf16 v[4:7], v[202:205], v[230:233], v[4:7]
	v_mfma_f32_16x16x32_bf16 v[8:11], v[194:197], v[230:233], v[8:11]
	v_mfma_f32_16x16x32_bf16 v[56:59], v[198:201], v[218:221], v[56:59]
	v_mfma_f32_16x16x32_bf16 v[52:55], v[206:209], v[218:221], v[52:55]
	v_mfma_f32_16x16x32_bf16 v[36:39], v[206:209], v[222:225], v[36:39]
	v_mfma_f32_16x16x32_bf16 v[40:43], v[198:201], v[222:225], v[40:43]
	v_mfma_f32_16x16x32_bf16 v[24:27], v[198:201], v[234:237], v[24:27]
	v_mfma_f32_16x16x32_bf16 v[20:23], v[206:209], v[234:237], v[20:23]
	v_mfma_f32_16x16x32_bf16 v[4:7], v[206:209], v[238:241], v[4:7]
	v_mfma_f32_16x16x32_bf16 v[8:11], v[198:201], v[238:241], v[8:11]
	s_barrier
	s_add_i32 s83, s83, 2
	s_add_u32 s68, s68, 0x100
	s_addc_u32 s69, s69, 0
	s_cmp_gt_u32 s83, 13
.LBB0_1135:
	ds_read_b128 v[168:171], v145
	ds_read_b128 v[174:177], v146
	ds_read_b128 v[178:181], v147
	ds_read_b128 v[182:185], v148
	ds_read_b128 v[194:197], v149
	ds_read_b128 v[198:201], v150
	ds_read_b128 v[202:205], v151
	ds_read_b128 v[206:209], v152
	s_add_u32 s70, s26, s68
	s_addc_u32 s71, s27, s69
	s_add_u32 s70, s70, 0x100
	s_addc_u32 s71, s71, 0
	s_add_u32 s84, s81, s68
	s_addc_u32 s85, s82, s69
	s_cmpk_eq_i32 s68, 0x700
	s_cselect_b32 s85, s59, s85
	s_cselect_b32 s84, s80, s84
	s_cselect_b32 s71, s57, s71
	s_cselect_b32 s70, s79, s70
	v_lshl_add_u64 v[140:141], v[138:139], 0, s[68:69]
	v_lshl_add_u64 v[242:243], v[140:141], 0, s[22:23]
	s_add_i32 m0, s34, 0x8000
	s_mov_b64 s[86:87], 0x20080
	ds_read_b128 v[210:213], v153
	ds_read_b128 v[214:217], v153 offset:2048
	ds_read_b128 v[218:221], v154
	ds_read_b128 v[222:225], v154 offset:2048
	ds_read_b128 v[226:229], v153 offset:4096
	ds_read_b128 v[230:233], v153 offset:6144
	ds_read_b128 v[234:237], v154 offset:4096
	ds_read_b128 v[238:241], v154 offset:6144
	global_load_lds_dwordx4 v[242:243], off
	v_lshl_add_u64 v[242:243], v[140:141], 0, s[86:87]
	s_add_i32 m0, s34, 0xa000
	s_mov_b64 s[86:87], 0x60080
	global_load_lds_dwordx4 v[242:243], off
	v_lshl_add_u64 v[242:243], v[140:141], 0, s[24:25]
	s_add_i32 m0, s34, 0xc000
	v_lshl_add_u64 v[140:141], v[140:141], 0, s[86:87]
	global_load_lds_dwordx4 v[242:243], off
	s_add_i32 m0, s34, 0xe000
	s_nop 0
	global_load_lds_dwordx4 v[140:141], off
	s_waitcnt vmcnt(8)
	s_waitcnt lgkmcnt(0)
	s_barrier
	v_mfma_f32_16x16x32_bf16 v[128:131], v[168:171], v[210:213], v[128:131]
	v_mfma_f32_16x16x32_bf16 v[124:127], v[178:181], v[210:213], v[124:127]
	v_mfma_f32_16x16x32_bf16 v[108:111], v[178:181], v[214:217], v[108:111]
	v_mfma_f32_16x16x32_bf16 v[112:115], v[168:171], v[214:217], v[112:115]
	v_mfma_f32_16x16x32_bf16 v[96:99], v[168:171], v[226:229], v[96:99]
	v_mfma_f32_16x16x32_bf16 v[92:95], v[178:181], v[226:229], v[92:95]
	v_mfma_f32_16x16x32_bf16 v[76:79], v[178:181], v[230:233], v[76:79]
	v_mfma_f32_16x16x32_bf16 v[80:83], v[168:171], v[230:233], v[80:83]
	v_mfma_f32_16x16x32_bf16 v[128:131], v[174:177], v[218:221], v[128:131]
	v_mfma_f32_16x16x32_bf16 v[124:127], v[182:185], v[218:221], v[124:127]
	v_mfma_f32_16x16x32_bf16 v[108:111], v[182:185], v[222:225], v[108:111]
	v_mfma_f32_16x16x32_bf16 v[112:115], v[174:177], v[222:225], v[112:115]
	v_mfma_f32_16x16x32_bf16 v[96:99], v[174:177], v[234:237], v[96:99]
	v_mfma_f32_16x16x32_bf16 v[92:95], v[182:185], v[234:237], v[92:95]
	v_mfma_f32_16x16x32_bf16 v[76:79], v[182:185], v[238:241], v[76:79]
	v_mfma_f32_16x16x32_bf16 v[80:83], v[174:177], v[238:241], v[80:83]
	v_mfma_f32_16x16x32_bf16 v[120:123], v[194:197], v[210:213], v[120:123]
	v_mfma_f32_16x16x32_bf16 v[116:119], v[202:205], v[210:213], v[116:119]
	v_mfma_f32_16x16x32_bf16 v[100:103], v[202:205], v[214:217], v[100:103]
	v_mfma_f32_16x16x32_bf16 v[104:107], v[194:197], v[214:217], v[104:107]
	v_mfma_f32_16x16x32_bf16 v[88:91], v[194:197], v[226:229], v[88:91]
	v_mfma_f32_16x16x32_bf16 v[84:87], v[202:205], v[226:229], v[84:87]
	v_mfma_f32_16x16x32_bf16 v[68:71], v[202:205], v[230:233], v[68:71]
	v_mfma_f32_16x16x32_bf16 v[72:75], v[194:197], v[230:233], v[72:75]
	v_mfma_f32_16x16x32_bf16 v[120:123], v[198:201], v[218:221], v[120:123]
	v_mfma_f32_16x16x32_bf16 v[116:119], v[206:209], v[218:221], v[116:119]
	v_mfma_f32_16x16x32_bf16 v[100:103], v[206:209], v[222:225], v[100:103]
	v_mfma_f32_16x16x32_bf16 v[104:107], v[198:201], v[222:225], v[104:107]
	v_mfma_f32_16x16x32_bf16 v[88:91], v[198:201], v[234:237], v[88:91]
	v_mfma_f32_16x16x32_bf16 v[84:87], v[206:209], v[234:237], v[84:87]
	v_mfma_f32_16x16x32_bf16 v[68:71], v[206:209], v[238:241], v[68:71]
	v_mfma_f32_16x16x32_bf16 v[72:75], v[198:201], v[238:241], v[72:75]
	s_barrier
	v_lshl_add_u64 v[140:141], s[84:85], 0, v[158:159]
	s_add_i32 s84, s67, s3
	s_mov_b32 m0, s84
	ds_read_b128 v[210:213], v153 offset:16384
	ds_read_b128 v[214:217], v153 offset:18432
	ds_read_b128 v[218:221], v154 offset:16384
	ds_read_b128 v[222:225], v154 offset:18432
	ds_read_b128 v[226:229], v153 offset:20480
	ds_read_b128 v[230:233], v153 offset:22528
	ds_read_b128 v[234:237], v154 offset:20480
	ds_read_b128 v[238:241], v154 offset:22528
	global_load_lds_dwordx4 v[140:141], off
	v_lshl_add_u64 v[242:243], v[140:141], 0, s[0:1]
	s_add_i32 m0, s84, 0x2000
	s_add_i32 s84, s72, s3
	global_load_lds_dwordx4 v[242:243], off
	v_lshl_add_u64 v[242:243], v[140:141], 0, s[12:13]
	s_mov_b32 m0, s84
	s_nop 0
	global_load_lds_dwordx4 v[242:243], off
	v_lshl_add_u64 v[242:243], v[140:141], 0, s[14:15]
	s_add_i32 m0, s84, 0x2000
	s_nop 0
	global_load_lds_dwordx4 v[242:243], off
	s_waitcnt vmcnt(4)
	s_waitcnt lgkmcnt(0)
	s_barrier
	v_mfma_f32_16x16x32_bf16 v[64:67], v[168:171], v[210:213], v[64:67]
	v_mfma_f32_16x16x32_bf16 v[60:63], v[178:181], v[210:213], v[60:63]
	v_mfma_f32_16x16x32_bf16 v[44:47], v[178:181], v[214:217], v[44:47]
	v_mfma_f32_16x16x32_bf16 v[48:51], v[168:171], v[214:217], v[48:51]
	v_mfma_f32_16x16x32_bf16 v[32:35], v[168:171], v[226:229], v[32:35]
	v_mfma_f32_16x16x32_bf16 v[28:31], v[178:181], v[226:229], v[28:31]
	v_mfma_f32_16x16x32_bf16 v[12:15], v[178:181], v[230:233], v[12:15]
	v_mfma_f32_16x16x32_bf16 v[16:19], v[168:171], v[230:233], v[16:19]
	v_mfma_f32_16x16x32_bf16 v[64:67], v[174:177], v[218:221], v[64:67]
	v_mfma_f32_16x16x32_bf16 v[60:63], v[182:185], v[218:221], v[60:63]
	v_mfma_f32_16x16x32_bf16 v[44:47], v[182:185], v[222:225], v[44:47]
	v_mfma_f32_16x16x32_bf16 v[48:51], v[174:177], v[222:225], v[48:51]
	v_mfma_f32_16x16x32_bf16 v[32:35], v[174:177], v[234:237], v[32:35]
	v_mfma_f32_16x16x32_bf16 v[28:31], v[182:185], v[234:237], v[28:31]
	v_mfma_f32_16x16x32_bf16 v[12:15], v[182:185], v[238:241], v[12:15]
	v_mfma_f32_16x16x32_bf16 v[16:19], v[174:177], v[238:241], v[16:19]
	v_mfma_f32_16x16x32_bf16 v[56:59], v[194:197], v[210:213], v[56:59]
	v_mfma_f32_16x16x32_bf16 v[52:55], v[202:205], v[210:213], v[52:55]
	v_mfma_f32_16x16x32_bf16 v[36:39], v[202:205], v[214:217], v[36:39]
	v_mfma_f32_16x16x32_bf16 v[40:43], v[194:197], v[214:217], v[40:43]
	v_mfma_f32_16x16x32_bf16 v[24:27], v[194:197], v[226:229], v[24:27]
	v_mfma_f32_16x16x32_bf16 v[20:23], v[202:205], v[226:229], v[20:23]
	v_mfma_f32_16x16x32_bf16 v[4:7], v[202:205], v[230:233], v[4:7]
	v_mfma_f32_16x16x32_bf16 v[8:11], v[194:197], v[230:233], v[8:11]
	v_mfma_f32_16x16x32_bf16 v[56:59], v[198:201], v[218:221], v[56:59]
	v_mfma_f32_16x16x32_bf16 v[52:55], v[206:209], v[218:221], v[52:55]
	v_mfma_f32_16x16x32_bf16 v[36:39], v[206:209], v[222:225], v[36:39]
	v_mfma_f32_16x16x32_bf16 v[40:43], v[198:201], v[222:225], v[40:43]
	v_mfma_f32_16x16x32_bf16 v[24:27], v[198:201], v[234:237], v[24:27]
	v_mfma_f32_16x16x32_bf16 v[20:23], v[206:209], v[234:237], v[20:23]
	v_mfma_f32_16x16x32_bf16 v[4:7], v[206:209], v[238:241], v[4:7]
	v_mfma_f32_16x16x32_bf16 v[8:11], v[198:201], v[238:241], v[8:11]
	s_barrier
	ds_read_b128 v[168:171], v163
	ds_read_b128 v[174:177], v164
	ds_read_b128 v[178:181], v155
	ds_read_b128 v[182:185], v160
	ds_read_b128 v[194:197], v165
	ds_read_b128 v[198:201], v166
	ds_read_b128 v[202:205], v161
	ds_read_b128 v[206:209], v162
	s_mov_b32 m0, s34
	v_lshl_add_u64 v[242:243], s[70:71], 0, v[0:1]
	ds_read_b128 v[210:213], v153 offset:32768
	ds_read_b128 v[214:217], v153 offset:34816
	ds_read_b128 v[218:221], v154 offset:32768
	ds_read_b128 v[222:225], v154 offset:34816
	ds_read_b128 v[226:229], v153 offset:36864
	ds_read_b128 v[230:233], v153 offset:38912
	ds_read_b128 v[234:237], v154 offset:36864
	ds_read_b128 v[238:241], v154 offset:38912
	global_load_lds_dwordx4 v[242:243], off
	v_lshl_add_u64 v[244:245], v[242:243], 0, s[16:17]
	s_mov_b32 m0, s35
	s_nop 0
	global_load_lds_dwordx4 v[244:245], off
	v_lshl_add_u64 v[244:245], v[242:243], 0, s[0:1]
	s_mov_b32 m0, s38
	v_lshl_add_u64 v[242:243], v[242:243], 0, s[18:19]
	global_load_lds_dwordx4 v[244:245], off
	s_mov_b32 m0, s39
	s_nop 0
	global_load_lds_dwordx4 v[242:243], off
	s_waitcnt vmcnt(8)
	s_waitcnt lgkmcnt(0)
	s_barrier
	v_mfma_f32_16x16x32_bf16 v[128:131], v[168:171], v[210:213], v[128:131]
	v_mfma_f32_16x16x32_bf16 v[124:127], v[178:181], v[210:213], v[124:127]
	v_mfma_f32_16x16x32_bf16 v[108:111], v[178:181], v[214:217], v[108:111]
	v_mfma_f32_16x16x32_bf16 v[112:115], v[168:171], v[214:217], v[112:115]
	v_mfma_f32_16x16x32_bf16 v[96:99], v[168:171], v[226:229], v[96:99]
	v_mfma_f32_16x16x32_bf16 v[92:95], v[178:181], v[226:229], v[92:95]
	v_mfma_f32_16x16x32_bf16 v[76:79], v[178:181], v[230:233], v[76:79]
	v_mfma_f32_16x16x32_bf16 v[80:83], v[168:171], v[230:233], v[80:83]
	v_mfma_f32_16x16x32_bf16 v[128:131], v[174:177], v[218:221], v[128:131]
	v_mfma_f32_16x16x32_bf16 v[124:127], v[182:185], v[218:221], v[124:127]
	v_mfma_f32_16x16x32_bf16 v[108:111], v[182:185], v[222:225], v[108:111]
	v_mfma_f32_16x16x32_bf16 v[112:115], v[174:177], v[222:225], v[112:115]
	v_mfma_f32_16x16x32_bf16 v[96:99], v[174:177], v[234:237], v[96:99]
	v_mfma_f32_16x16x32_bf16 v[92:95], v[182:185], v[234:237], v[92:95]
	v_mfma_f32_16x16x32_bf16 v[76:79], v[182:185], v[238:241], v[76:79]
	v_mfma_f32_16x16x32_bf16 v[80:83], v[174:177], v[238:241], v[80:83]
	v_mfma_f32_16x16x32_bf16 v[120:123], v[194:197], v[210:213], v[120:123]
	v_mfma_f32_16x16x32_bf16 v[116:119], v[202:205], v[210:213], v[116:119]
	v_mfma_f32_16x16x32_bf16 v[100:103], v[202:205], v[214:217], v[100:103]
	v_mfma_f32_16x16x32_bf16 v[104:107], v[194:197], v[214:217], v[104:107]
	v_mfma_f32_16x16x32_bf16 v[88:91], v[194:197], v[226:229], v[88:91]
	v_mfma_f32_16x16x32_bf16 v[84:87], v[202:205], v[226:229], v[84:87]
	v_mfma_f32_16x16x32_bf16 v[68:71], v[202:205], v[230:233], v[68:71]
	v_mfma_f32_16x16x32_bf16 v[72:75], v[194:197], v[230:233], v[72:75]
	v_mfma_f32_16x16x32_bf16 v[120:123], v[198:201], v[218:221], v[120:123]
	v_mfma_f32_16x16x32_bf16 v[116:119], v[206:209], v[218:221], v[116:119]
	v_mfma_f32_16x16x32_bf16 v[100:103], v[206:209], v[222:225], v[100:103]
	v_mfma_f32_16x16x32_bf16 v[104:107], v[198:201], v[222:225], v[104:107]
	v_mfma_f32_16x16x32_bf16 v[88:91], v[198:201], v[234:237], v[88:91]
	v_mfma_f32_16x16x32_bf16 v[84:87], v[206:209], v[234:237], v[84:87]
	v_mfma_f32_16x16x32_bf16 v[68:71], v[206:209], v[238:241], v[68:71]
	v_mfma_f32_16x16x32_bf16 v[72:75], v[198:201], v[238:241], v[72:75]
	s_barrier
	s_add_i32 s70, s73, s3
	v_lshl_add_u64 v[242:243], v[140:141], 0, s[22:23]
	s_mov_b32 m0, s70
	ds_read_b128 v[210:213], v153 offset:49152
	ds_read_b128 v[214:217], v153 offset:51200
	ds_read_b128 v[218:221], v154 offset:49152
	ds_read_b128 v[222:225], v154 offset:51200
	ds_read_b128 v[226:229], v153 offset:53248
	ds_read_b128 v[230:233], v153 offset:55296
	ds_read_b128 v[234:237], v154 offset:53248
	ds_read_b128 v[238:241], v154 offset:55296
	global_load_lds_dwordx4 v[242:243], off
	v_lshl_add_u64 v[242:243], v[140:141], 0, s[24:25]
	s_add_i32 m0, s70, 0x2000
	s_add_i32 s70, s77, s3
	global_load_lds_dwordx4 v[242:243], off
	v_lshl_add_u64 v[242:243], v[140:141], 0, s[28:29]
	s_mov_b32 m0, s70
	v_lshl_add_u64 v[140:141], v[140:141], 0, s[36:37]
	global_load_lds_dwordx4 v[242:243], off
	s_add_i32 m0, s70, 0x2000
	s_nop 0
	global_load_lds_dwordx4 v[140:141], off
	s_waitcnt vmcnt(4)
	s_waitcnt lgkmcnt(0)
	s_barrier
	v_mfma_f32_16x16x32_bf16 v[64:67], v[168:171], v[210:213], v[64:67]
	v_mfma_f32_16x16x32_bf16 v[60:63], v[178:181], v[210:213], v[60:63]
	v_mfma_f32_16x16x32_bf16 v[44:47], v[178:181], v[214:217], v[44:47]
	v_mfma_f32_16x16x32_bf16 v[48:51], v[168:171], v[214:217], v[48:51]
	v_mfma_f32_16x16x32_bf16 v[32:35], v[168:171], v[226:229], v[32:35]
	v_mfma_f32_16x16x32_bf16 v[28:31], v[178:181], v[226:229], v[28:31]
	v_mfma_f32_16x16x32_bf16 v[12:15], v[178:181], v[230:233], v[12:15]
	v_mfma_f32_16x16x32_bf16 v[16:19], v[168:171], v[230:233], v[16:19]
	v_mfma_f32_16x16x32_bf16 v[64:67], v[174:177], v[218:221], v[64:67]
	v_mfma_f32_16x16x32_bf16 v[60:63], v[182:185], v[218:221], v[60:63]
	v_mfma_f32_16x16x32_bf16 v[44:47], v[182:185], v[222:225], v[44:47]
	v_mfma_f32_16x16x32_bf16 v[48:51], v[174:177], v[222:225], v[48:51]
	v_mfma_f32_16x16x32_bf16 v[32:35], v[174:177], v[234:237], v[32:35]
	v_mfma_f32_16x16x32_bf16 v[28:31], v[182:185], v[234:237], v[28:31]
	v_mfma_f32_16x16x32_bf16 v[12:15], v[182:185], v[238:241], v[12:15]
	v_mfma_f32_16x16x32_bf16 v[16:19], v[174:177], v[238:241], v[16:19]
	v_mfma_f32_16x16x32_bf16 v[56:59], v[194:197], v[210:213], v[56:59]
	v_mfma_f32_16x16x32_bf16 v[52:55], v[202:205], v[210:213], v[52:55]
	v_mfma_f32_16x16x32_bf16 v[36:39], v[202:205], v[214:217], v[36:39]
	v_mfma_f32_16x16x32_bf16 v[40:43], v[194:197], v[214:217], v[40:43]
	v_mfma_f32_16x16x32_bf16 v[24:27], v[194:197], v[226:229], v[24:27]
	v_mfma_f32_16x16x32_bf16 v[20:23], v[202:205], v[226:229], v[20:23]
	v_mfma_f32_16x16x32_bf16 v[4:7], v[202:205], v[230:233], v[4:7]
	v_mfma_f32_16x16x32_bf16 v[8:11], v[194:197], v[230:233], v[8:11]
	v_mfma_f32_16x16x32_bf16 v[56:59], v[198:201], v[218:221], v[56:59]
	v_mfma_f32_16x16x32_bf16 v[52:55], v[206:209], v[218:221], v[52:55]
	v_mfma_f32_16x16x32_bf16 v[36:39], v[206:209], v[222:225], v[36:39]
	v_mfma_f32_16x16x32_bf16 v[40:43], v[198:201], v[222:225], v[40:43]
	v_mfma_f32_16x16x32_bf16 v[24:27], v[198:201], v[234:237], v[24:27]
	v_mfma_f32_16x16x32_bf16 v[20:23], v[206:209], v[234:237], v[20:23]
	v_mfma_f32_16x16x32_bf16 v[4:7], v[206:209], v[238:241], v[4:7]
	v_mfma_f32_16x16x32_bf16 v[8:11], v[198:201], v[238:241], v[8:11]
	s_barrier
	s_add_i32 s83, s83, 2
	s_add_u32 s68, s68, 0x100
	s_addc_u32 s69, s69, 0
	s_cmp_gt_u32 s83, 13
	s_cbranch_scc0 .LBB0_1135
	s_and_b64 vcc, exec, s[40:41]
	s_cbranch_vccz .LBB0_1138
	s_barrier

.LBB0_1371:
	v_add_u32_e32 v147, s64, v143
	v_add_u32_e32 v152, s64, v144
	ds_read_b128 v[148:151], v147
	ds_read_b128 v[152:155], v152
	v_add_u32_e32 v147, s65, v143
	v_add_u32_e32 v162, s65, v144
	s_add_u32 s58, s18, s56
	ds_read_b128 v[158:161], v147
	ds_read_b128 v[162:165], v162
	v_add_u32_e32 v147, s66, v143
	s_addc_u32 s59, s19, s57
	v_add_u32_e32 v166, s66, v144
	ds_read_b128 v[170:173], v147
	ds_read_b128 v[174:177], v166
	v_add_u32_e32 v147, s67, v143
	s_add_u32 s58, s58, 0x100
	v_add_u32_e32 v166, s67, v144
	ds_read_b128 v[178:181], v147
	ds_read_b128 v[182:185], v166
	s_addc_u32 s59, s59, 0
	s_add_u32 s78, s53, s56
	s_addc_u32 s79, s72, s57
	s_cmpk_eq_i32 s56, 0x1f00
	s_cselect_b32 s79, s49, s79
	s_cselect_b32 s78, s76, s78
	s_cselect_b32 s59, s51, s59
	s_cselect_b32 s58, s73, s58
	v_lshl_add_u64 v[166:167], v[140:141], 0, s[56:57]
	v_lshl_add_u64 v[218:219], v[166:167], 0, s[24:25]
	s_add_i32 m0, s35, 0x8000
	ds_read_b128 v[186:189], v145
	ds_read_b128 v[190:193], v145 offset:2048
	ds_read_b128 v[194:197], v146
	ds_read_b128 v[198:201], v146 offset:2048
	ds_read_b128 v[202:205], v145 offset:4096
	ds_read_b128 v[206:209], v145 offset:6144
	ds_read_b128 v[210:213], v146 offset:4096
	ds_read_b128 v[214:217], v146 offset:6144
	global_load_lds_dwordx4 v[218:219], off
	v_lshl_add_u64 v[218:219], v[166:167], 0, s[44:45]
	s_add_i32 m0, s35, 0xa000
	s_nop 0
	global_load_lds_dwordx4 v[218:219], off
	v_lshl_add_u64 v[218:219], v[166:167], 0, s[28:29]
	s_add_i32 m0, s35, 0xc000
	v_lshl_add_u64 v[166:167], v[166:167], 0, s[46:47]
	global_load_lds_dwordx4 v[218:219], off
	s_add_i32 m0, s35, 0xe000
	s_nop 0
	global_load_lds_dwordx4 v[166:167], off
	s_waitcnt vmcnt(8)
	s_waitcnt lgkmcnt(0)
	s_barrier
	v_mfma_f32_16x16x32_bf16 v[128:131], v[148:151], v[186:189], v[128:131]
	v_mfma_f32_16x16x32_bf16 v[124:127], v[158:161], v[186:189], v[124:127]
	v_mfma_f32_16x16x32_bf16 v[108:111], v[158:161], v[190:193], v[108:111]
	v_mfma_f32_16x16x32_bf16 v[112:115], v[148:151], v[190:193], v[112:115]
	v_mfma_f32_16x16x32_bf16 v[96:99], v[148:151], v[202:205], v[96:99]
	v_mfma_f32_16x16x32_bf16 v[92:95], v[158:161], v[202:205], v[92:95]
	v_mfma_f32_16x16x32_bf16 v[76:79], v[158:161], v[206:209], v[76:79]
	v_mfma_f32_16x16x32_bf16 v[80:83], v[148:151], v[206:209], v[80:83]
	v_mfma_f32_16x16x32_bf16 v[128:131], v[152:155], v[194:197], v[128:131]
	v_mfma_f32_16x16x32_bf16 v[124:127], v[162:165], v[194:197], v[124:127]
	v_mfma_f32_16x16x32_bf16 v[108:111], v[162:165], v[198:201], v[108:111]
	v_mfma_f32_16x16x32_bf16 v[112:115], v[152:155], v[198:201], v[112:115]
	v_mfma_f32_16x16x32_bf16 v[96:99], v[152:155], v[210:213], v[96:99]
	v_mfma_f32_16x16x32_bf16 v[92:95], v[162:165], v[210:213], v[92:95]
	v_mfma_f32_16x16x32_bf16 v[76:79], v[162:165], v[214:217], v[76:79]
	v_mfma_f32_16x16x32_bf16 v[80:83], v[152:155], v[214:217], v[80:83]
	v_mfma_f32_16x16x32_bf16 v[120:123], v[170:173], v[186:189], v[120:123]
	v_mfma_f32_16x16x32_bf16 v[116:119], v[178:181], v[186:189], v[116:119]
	v_mfma_f32_16x16x32_bf16 v[100:103], v[178:181], v[190:193], v[100:103]
	v_mfma_f32_16x16x32_bf16 v[104:107], v[170:173], v[190:193], v[104:107]
	v_mfma_f32_16x16x32_bf16 v[88:91], v[170:173], v[202:205], v[88:91]
	v_mfma_f32_16x16x32_bf16 v[84:87], v[178:181], v[202:205], v[84:87]
	v_mfma_f32_16x16x32_bf16 v[68:71], v[178:181], v[206:209], v[68:71]
	v_mfma_f32_16x16x32_bf16 v[72:75], v[170:173], v[206:209], v[72:75]
	v_mfma_f32_16x16x32_bf16 v[120:123], v[174:177], v[194:197], v[120:123]
	v_mfma_f32_16x16x32_bf16 v[116:119], v[182:185], v[194:197], v[116:119]
	v_mfma_f32_16x16x32_bf16 v[100:103], v[182:185], v[198:201], v[100:103]
	v_mfma_f32_16x16x32_bf16 v[104:107], v[174:177], v[198:201], v[104:107]
	v_mfma_f32_16x16x32_bf16 v[88:91], v[174:177], v[210:213], v[88:91]
	v_mfma_f32_16x16x32_bf16 v[84:87], v[182:185], v[210:213], v[84:87]
	v_mfma_f32_16x16x32_bf16 v[68:71], v[182:185], v[214:217], v[68:71]
	v_mfma_f32_16x16x32_bf16 v[72:75], v[174:177], v[214:217], v[72:75]
	s_barrier
	v_lshl_add_u64 v[166:167], s[78:79], 0, v[132:133]
	s_add_i32 s78, s64, s34
	s_mov_b32 m0, s78
	ds_read_b128 v[186:189], v145 offset:16384
	ds_read_b128 v[190:193], v145 offset:18432
	ds_read_b128 v[194:197], v146 offset:16384
	ds_read_b128 v[198:201], v146 offset:18432
	ds_read_b128 v[202:205], v145 offset:20480
	ds_read_b128 v[206:209], v145 offset:22528
	ds_read_b128 v[210:213], v146 offset:20480
	ds_read_b128 v[214:217], v146 offset:22528
	global_load_lds_dwordx4 v[166:167], off
	v_lshl_add_u64 v[218:219], v[166:167], 0, s[10:11]
	s_add_i32 m0, s78, 0x2000
	s_add_i32 s78, s66, s34
	global_load_lds_dwordx4 v[218:219], off
	v_lshl_add_u64 v[218:219], v[166:167], 0, s[14:15]
	s_mov_b32 m0, s78
	s_nop 0
	global_load_lds_dwordx4 v[218:219], off
	v_lshl_add_u64 v[218:219], v[166:167], 0, s[16:17]
	s_add_i32 m0, s78, 0x2000
	s_nop 0
	global_load_lds_dwordx4 v[218:219], off
	s_waitcnt vmcnt(4)
	s_waitcnt lgkmcnt(0)
	s_barrier
	v_mfma_f32_16x16x32_bf16 v[64:67], v[148:151], v[186:189], v[64:67]
	v_mfma_f32_16x16x32_bf16 v[60:63], v[158:161], v[186:189], v[60:63]
	v_mfma_f32_16x16x32_bf16 v[44:47], v[158:161], v[190:193], v[44:47]
	v_mfma_f32_16x16x32_bf16 v[48:51], v[148:151], v[190:193], v[48:51]
	v_mfma_f32_16x16x32_bf16 v[32:35], v[148:151], v[202:205], v[32:35]
	v_mfma_f32_16x16x32_bf16 v[28:31], v[158:161], v[202:205], v[28:31]
	v_mfma_f32_16x16x32_bf16 v[12:15], v[158:161], v[206:209], v[12:15]
	v_mfma_f32_16x16x32_bf16 v[16:19], v[148:151], v[206:209], v[16:19]
	v_mfma_f32_16x16x32_bf16 v[64:67], v[152:155], v[194:197], v[64:67]
	v_mfma_f32_16x16x32_bf16 v[60:63], v[162:165], v[194:197], v[60:63]
	v_mfma_f32_16x16x32_bf16 v[44:47], v[162:165], v[198:201], v[44:47]
	v_mfma_f32_16x16x32_bf16 v[48:51], v[152:155], v[198:201], v[48:51]
	v_mfma_f32_16x16x32_bf16 v[32:35], v[152:155], v[210:213], v[32:35]
	v_mfma_f32_16x16x32_bf16 v[28:31], v[162:165], v[210:213], v[28:31]
	v_mfma_f32_16x16x32_bf16 v[12:15], v[162:165], v[214:217], v[12:15]
	v_mfma_f32_16x16x32_bf16 v[16:19], v[152:155], v[214:217], v[16:19]
	v_mfma_f32_16x16x32_bf16 v[56:59], v[170:173], v[186:189], v[56:59]
	v_mfma_f32_16x16x32_bf16 v[52:55], v[178:181], v[186:189], v[52:55]
	v_mfma_f32_16x16x32_bf16 v[36:39], v[178:181], v[190:193], v[36:39]
	v_mfma_f32_16x16x32_bf16 v[40:43], v[170:173], v[190:193], v[40:43]
	v_mfma_f32_16x16x32_bf16 v[24:27], v[170:173], v[202:205], v[24:27]
	v_mfma_f32_16x16x32_bf16 v[20:23], v[178:181], v[202:205], v[20:23]
	v_mfma_f32_16x16x32_bf16 v[4:7], v[178:181], v[206:209], v[4:7]
	v_mfma_f32_16x16x32_bf16 v[8:11], v[170:173], v[206:209], v[8:11]
	v_mfma_f32_16x16x32_bf16 v[56:59], v[174:177], v[194:197], v[56:59]
	v_mfma_f32_16x16x32_bf16 v[52:55], v[182:185], v[194:197], v[52:55]
	v_mfma_f32_16x16x32_bf16 v[36:39], v[182:185], v[198:201], v[36:39]
	v_mfma_f32_16x16x32_bf16 v[40:43], v[174:177], v[198:201], v[40:43]
	v_mfma_f32_16x16x32_bf16 v[24:27], v[174:177], v[210:213], v[24:27]
	v_mfma_f32_16x16x32_bf16 v[20:23], v[182:185], v[210:213], v[20:23]
	v_mfma_f32_16x16x32_bf16 v[4:7], v[182:185], v[214:217], v[4:7]
	v_mfma_f32_16x16x32_bf16 v[8:11], v[174:177], v[214:217], v[8:11]
	s_barrier
	v_add_u32_e32 v147, s70, v143
	v_add_u32_e32 v152, s70, v144
	ds_read_b128 v[148:151], v147
	ds_read_b128 v[152:155], v152
	v_add_u32_e32 v147, s68, v143
	v_add_u32_e32 v162, s68, v144
	ds_read_b128 v[158:161], v147
	ds_read_b128 v[162:165], v162
	v_add_u32_e32 v147, s71, v143
	v_add_u32_e32 v169, s71, v144
	ds_read_b128 v[170:173], v147
	ds_read_b128 v[174:177], v169
	v_add_u32_e32 v147, s69, v143
	v_add_u32_e32 v169, s69, v144
	ds_read_b128 v[178:181], v147
	ds_read_b128 v[182:185], v169
	s_mov_b32 m0, s35
	v_lshl_add_u64 v[218:219], s[58:59], 0, v[0:1]
	ds_read_b128 v[186:189], v145 offset:32768
	ds_read_b128 v[190:193], v145 offset:34816
	ds_read_b128 v[194:197], v146 offset:32768
	ds_read_b128 v[198:201], v146 offset:34816
	ds_read_b128 v[202:205], v145 offset:36864
	ds_read_b128 v[206:209], v145 offset:38912
	ds_read_b128 v[210:213], v146 offset:36864
	ds_read_b128 v[214:217], v146 offset:38912
	global_load_lds_dwordx4 v[218:219], off
	v_lshl_add_u64 v[220:221], v[218:219], 0, s[20:21]
	s_mov_b32 m0, s39
	s_nop 0
	global_load_lds_dwordx4 v[220:221], off
	v_lshl_add_u64 v[220:221], v[218:219], 0, s[10:11]
	s_mov_b32 m0, s60
	v_lshl_add_u64 v[218:219], v[218:219], 0, s[22:23]
	global_load_lds_dwordx4 v[220:221], off
	s_mov_b32 m0, s61
	s_nop 0
	global_load_lds_dwordx4 v[218:219], off
	s_waitcnt vmcnt(8)
	s_waitcnt lgkmcnt(0)
	s_barrier
	v_mfma_f32_16x16x32_bf16 v[128:131], v[148:151], v[186:189], v[128:131]
	v_mfma_f32_16x16x32_bf16 v[124:127], v[158:161], v[186:189], v[124:127]
	v_mfma_f32_16x16x32_bf16 v[108:111], v[158:161], v[190:193], v[108:111]
	v_mfma_f32_16x16x32_bf16 v[112:115], v[148:151], v[190:193], v[112:115]
	v_mfma_f32_16x16x32_bf16 v[96:99], v[148:151], v[202:205], v[96:99]
	v_mfma_f32_16x16x32_bf16 v[92:95], v[158:161], v[202:205], v[92:95]
	v_mfma_f32_16x16x32_bf16 v[76:79], v[158:161], v[206:209], v[76:79]
	v_mfma_f32_16x16x32_bf16 v[80:83], v[148:151], v[206:209], v[80:83]
	v_mfma_f32_16x16x32_bf16 v[128:131], v[152:155], v[194:197], v[128:131]
	v_mfma_f32_16x16x32_bf16 v[124:127], v[162:165], v[194:197], v[124:127]
	v_mfma_f32_16x16x32_bf16 v[108:111], v[162:165], v[198:201], v[108:111]
	v_mfma_f32_16x16x32_bf16 v[112:115], v[152:155], v[198:201], v[112:115]
	v_mfma_f32_16x16x32_bf16 v[96:99], v[152:155], v[210:213], v[96:99]
	v_mfma_f32_16x16x32_bf16 v[92:95], v[162:165], v[210:213], v[92:95]
	v_mfma_f32_16x16x32_bf16 v[76:79], v[162:165], v[214:217], v[76:79]
	v_mfma_f32_16x16x32_bf16 v[80:83], v[152:155], v[214:217], v[80:83]
	v_mfma_f32_16x16x32_bf16 v[120:123], v[170:173], v[186:189], v[120:123]
	v_mfma_f32_16x16x32_bf16 v[116:119], v[178:181], v[186:189], v[116:119]
	v_mfma_f32_16x16x32_bf16 v[100:103], v[178:181], v[190:193], v[100:103]
	v_mfma_f32_16x16x32_bf16 v[104:107], v[170:173], v[190:193], v[104:107]
	v_mfma_f32_16x16x32_bf16 v[88:91], v[170:173], v[202:205], v[88:91]
	v_mfma_f32_16x16x32_bf16 v[84:87], v[178:181], v[202:205], v[84:87]
	v_mfma_f32_16x16x32_bf16 v[68:71], v[178:181], v[206:209], v[68:71]
	v_mfma_f32_16x16x32_bf16 v[72:75], v[170:173], v[206:209], v[72:75]
	v_mfma_f32_16x16x32_bf16 v[120:123], v[174:177], v[194:197], v[120:123]
	v_mfma_f32_16x16x32_bf16 v[116:119], v[182:185], v[194:197], v[116:119]
	v_mfma_f32_16x16x32_bf16 v[100:103], v[182:185], v[198:201], v[100:103]
	v_mfma_f32_16x16x32_bf16 v[104:107], v[174:177], v[198:201], v[104:107]
	v_mfma_f32_16x16x32_bf16 v[88:91], v[174:177], v[210:213], v[88:91]
	v_mfma_f32_16x16x32_bf16 v[84:87], v[182:185], v[210:213], v[84:87]
	v_mfma_f32_16x16x32_bf16 v[68:71], v[182:185], v[214:217], v[68:71]
	v_mfma_f32_16x16x32_bf16 v[72:75], v[174:177], v[214:217], v[72:75]
	s_barrier
	s_add_i32 s58, s70, s34
	v_lshl_add_u64 v[218:219], v[166:167], 0, s[24:25]
	s_mov_b32 m0, s58
	ds_read_b128 v[186:189], v145 offset:49152
	ds_read_b128 v[190:193], v145 offset:51200
	ds_read_b128 v[194:197], v146 offset:49152
	ds_read_b128 v[198:201], v146 offset:51200
	ds_read_b128 v[202:205], v145 offset:53248
	ds_read_b128 v[206:209], v145 offset:55296
	ds_read_b128 v[210:213], v146 offset:53248
	ds_read_b128 v[214:217], v146 offset:55296
	global_load_lds_dwordx4 v[218:219], off
	v_lshl_add_u64 v[218:219], v[166:167], 0, s[28:29]
	s_add_i32 m0, s58, 0x2000
	s_add_i32 s58, s71, s34
	global_load_lds_dwordx4 v[218:219], off
	v_lshl_add_u64 v[218:219], v[166:167], 0, s[36:37]
	s_mov_b32 m0, s58
	v_lshl_add_u64 v[166:167], v[166:167], 0, s[40:41]
	global_load_lds_dwordx4 v[218:219], off
	s_add_i32 m0, s58, 0x2000
	s_nop 0
	global_load_lds_dwordx4 v[166:167], off
	s_waitcnt vmcnt(4)
	s_waitcnt lgkmcnt(0)
	s_barrier
	v_mfma_f32_16x16x32_bf16 v[64:67], v[148:151], v[186:189], v[64:67]
	v_mfma_f32_16x16x32_bf16 v[60:63], v[158:161], v[186:189], v[60:63]
	v_mfma_f32_16x16x32_bf16 v[44:47], v[158:161], v[190:193], v[44:47]
	v_mfma_f32_16x16x32_bf16 v[48:51], v[148:151], v[190:193], v[48:51]
	v_mfma_f32_16x16x32_bf16 v[32:35], v[148:151], v[202:205], v[32:35]
	v_mfma_f32_16x16x32_bf16 v[28:31], v[158:161], v[202:205], v[28:31]
	v_mfma_f32_16x16x32_bf16 v[12:15], v[158:161], v[206:209], v[12:15]
	v_mfma_f32_16x16x32_bf16 v[16:19], v[148:151], v[206:209], v[16:19]
	v_mfma_f32_16x16x32_bf16 v[64:67], v[152:155], v[194:197], v[64:67]
	v_mfma_f32_16x16x32_bf16 v[60:63], v[162:165], v[194:197], v[60:63]
	v_mfma_f32_16x16x32_bf16 v[44:47], v[162:165], v[198:201], v[44:47]
	v_mfma_f32_16x16x32_bf16 v[48:51], v[152:155], v[198:201], v[48:51]
	v_mfma_f32_16x16x32_bf16 v[32:35], v[152:155], v[210:213], v[32:35]
	v_mfma_f32_16x16x32_bf16 v[28:31], v[162:165], v[210:213], v[28:31]
	v_mfma_f32_16x16x32_bf16 v[12:15], v[162:165], v[214:217], v[12:15]
	v_mfma_f32_16x16x32_bf16 v[16:19], v[152:155], v[214:217], v[16:19]
	v_mfma_f32_16x16x32_bf16 v[56:59], v[170:173], v[186:189], v[56:59]
	v_mfma_f32_16x16x32_bf16 v[52:55], v[178:181], v[186:189], v[52:55]
	v_mfma_f32_16x16x32_bf16 v[36:39], v[178:181], v[190:193], v[36:39]
	v_mfma_f32_16x16x32_bf16 v[40:43], v[170:173], v[190:193], v[40:43]
	v_mfma_f32_16x16x32_bf16 v[24:27], v[170:173], v[202:205], v[24:27]
	v_mfma_f32_16x16x32_bf16 v[20:23], v[178:181], v[202:205], v[20:23]
	v_mfma_f32_16x16x32_bf16 v[4:7], v[178:181], v[206:209], v[4:7]
	v_mfma_f32_16x16x32_bf16 v[8:11], v[170:173], v[206:209], v[8:11]
	v_mfma_f32_16x16x32_bf16 v[56:59], v[174:177], v[194:197], v[56:59]
	v_mfma_f32_16x16x32_bf16 v[52:55], v[182:185], v[194:197], v[52:55]
	v_mfma_f32_16x16x32_bf16 v[36:39], v[182:185], v[198:201], v[36:39]
	v_mfma_f32_16x16x32_bf16 v[40:43], v[174:177], v[198:201], v[40:43]
	v_mfma_f32_16x16x32_bf16 v[24:27], v[174:177], v[210:213], v[24:27]
	v_mfma_f32_16x16x32_bf16 v[20:23], v[182:185], v[210:213], v[20:23]
	v_mfma_f32_16x16x32_bf16 v[4:7], v[182:185], v[214:217], v[4:7]
	v_mfma_f32_16x16x32_bf16 v[8:11], v[174:177], v[214:217], v[8:11]
	s_barrier
	s_add_i32 s77, s77, 2
	s_add_u32 s56, s56, 0x100
	s_addc_u32 s57, s57, 0
	s_cmp_gt_u32 s77, 61
	s_cbranch_scc0 .LBB0_1371
	s_add_u32 s56, s53, 0xffffff00
	s_addc_u32 s57, s72, -1
	s_andn2_b64 vcc, exec, s[6:7]
	s_cbranch_vccnz .LBB0_1362
	v_mov_b32_e32 v4, 0
	s_mov_b32 s0, s48
	s_mov_b32 s8, s50
	s_mov_b64 s[18:19], s[54:55]
	s_mov_b32 s63, s52
	v_mov_b32_e32 v5, v4
	v_mov_b32_e32 v6, v4
	v_mov_b32_e32 v7, v4
	v_mov_b32_e32 v8, v4
	v_mov_b32_e32 v9, v4
	v_mov_b32_e32 v10, v4
	v_mov_b32_e32 v11, v4
	v_mov_b32_e32 v20, v4
	v_mov_b32_e32 v21, v4
	v_mov_b32_e32 v22, v4
	v_mov_b32_e32 v23, v4
	v_mov_b32_e32 v24, v4
	v_mov_b32_e32 v25, v4
	v_mov_b32_e32 v26, v4
	v_mov_b32_e32 v27, v4
	v_mov_b32_e32 v36, v4
	v_mov_b32_e32 v37, v4
	v_mov_b32_e32 v38, v4
	v_mov_b32_e32 v39, v4
	v_mov_b32_e32 v40, v4
	v_mov_b32_e32 v41, v4
	v_mov_b32_e32 v42, v4
	v_mov_b32_e32 v43, v4
	v_mov_b32_e32 v52, v4
	v_mov_b32_e32 v53, v4
	v_mov_b32_e32 v54, v4
	v_mov_b32_e32 v55, v4
	v_mov_b32_e32 v56, v4
	v_mov_b32_e32 v57, v4
	v_mov_b32_e32 v58, v4
	v_mov_b32_e32 v59, v4
	v_mov_b32_e32 v12, v4
	v_mov_b32_e32 v13, v4
	v_mov_b32_e32 v14, v4
	v_mov_b32_e32 v15, v4
	v_mov_b32_e32 v16, v4
	v_mov_b32_e32 v17, v4
	v_mov_b32_e32 v18, v4
	v_mov_b32_e32 v19, v4
	v_mov_b32_e32 v28, v4
	v_mov_b32_e32 v29, v4
	v_mov_b32_e32 v30, v4
	v_mov_b32_e32 v31, v4
	v_mov_b32_e32 v32, v4
	v_mov_b32_e32 v33, v4
	v_mov_b32_e32 v34, v4
	v_mov_b32_e32 v35, v4
	v_mov_b32_e32 v44, v4
	v_mov_b32_e32 v45, v4
	v_mov_b32_e32 v46, v4
	v_mov_b32_e32 v47, v4
	v_mov_b32_e32 v48, v4
	v_mov_b32_e32 v49, v4
	v_mov_b32_e32 v50, v4
	v_mov_b32_e32 v51, v4
	v_mov_b32_e32 v60, v4
	v_mov_b32_e32 v61, v4
	v_mov_b32_e32 v62, v4
	v_mov_b32_e32 v63, v4
	v_mov_b32_e32 v64, v4
	v_mov_b32_e32 v65, v4
	v_mov_b32_e32 v66, v4
	v_mov_b32_e32 v67, v4
	v_mov_b32_e32 v68, v4
	v_mov_b32_e32 v69, v4
	v_mov_b32_e32 v70, v4
	v_mov_b32_e32 v71, v4
	v_mov_b32_e32 v72, v4
	v_mov_b32_e32 v73, v4
	v_mov_b32_e32 v74, v4
	v_mov_b32_e32 v75, v4
	v_mov_b32_e32 v84, v4
	v_mov_b32_e32 v85, v4
	v_mov_b32_e32 v86, v4
	v_mov_b32_e32 v87, v4
	v_mov_b32_e32 v88, v4
	v_mov_b32_e32 v89, v4
	v_mov_b32_e32 v90, v4
	v_mov_b32_e32 v91, v4
	v_mov_b32_e32 v100, v4
	v_mov_b32_e32 v101, v4
	v_mov_b32_e32 v102, v4
	v_mov_b32_e32 v103, v4
	v_mov_b32_e32 v104, v4
	v_mov_b32_e32 v105, v4
	v_mov_b32_e32 v106, v4
	v_mov_b32_e32 v107, v4
	v_mov_b32_e32 v116, v4
	v_mov_b32_e32 v117, v4
	v_mov_b32_e32 v118, v4
	v_mov_b32_e32 v119, v4
	v_mov_b32_e32 v120, v4
	v_mov_b32_e32 v121, v4
	v_mov_b32_e32 v122, v4
	v_mov_b32_e32 v123, v4
	v_mov_b32_e32 v76, v4
	v_mov_b32_e32 v77, v4
	v_mov_b32_e32 v78, v4
	v_mov_b32_e32 v79, v4
	v_mov_b32_e32 v80, v4
	v_mov_b32_e32 v81, v4
	v_mov_b32_e32 v82, v4
	v_mov_b32_e32 v83, v4
	v_mov_b32_e32 v92, v4
	v_mov_b32_e32 v93, v4
	v_mov_b32_e32 v94, v4
	v_mov_b32_e32 v95, v4
	v_mov_b32_e32 v96, v4
	v_mov_b32_e32 v97, v4
	v_mov_b32_e32 v98, v4
	v_mov_b32_e32 v99, v4
	v_mov_b32_e32 v108, v4
	v_mov_b32_e32 v109, v4
	v_mov_b32_e32 v110, v4
	v_mov_b32_e32 v111, v4
	v_mov_b32_e32 v112, v4
	v_mov_b32_e32 v113, v4
	v_mov_b32_e32 v114, v4
	v_mov_b32_e32 v115, v4
	v_mov_b32_e32 v124, v4
	v_mov_b32_e32 v125, v4
	v_mov_b32_e32 v126, v4
	v_mov_b32_e32 v127, v4
	v_mov_b32_e32 v128, v4
	v_mov_b32_e32 v129, v4
	v_mov_b32_e32 v130, v4
	v_mov_b32_e32 v131, v4
	s_andn2_b64 vcc, exec, s[4:5]
	s_cbranch_vccnz .LBB0_1363
